# GEMM K loops: vmcnt(8) and lgkmcnt(0) before each pre-MFMA barrier merged into one s_waitcnt
# baseline (speedup 1.0000x reference)
; #define PG8_STAGE(bufoff, gbase, voff) do { _Pragma("unroll") for (int _i = 0; _i < 2; ++_i) \
;         __builtin_amdgcn_global_load_lds((const unsigned*)((const char*)(gbase) + (voff)[_i]), (PG8_LAS unsigned*)(lds + (bufoff) + ldsw + _i * 8192), 16, 0, 0); } while (0)
; #define PG8_LDA(dst, b, h) do { _Pragma("unroll") for (int m = 0; m < 4; ++m) _Pragma("unroll") for (int k = 0; k < 2; ++k) dst[m][k] = *(const PG8_LAS bf16x8*)(lds + PG8_SA(b, h) + aoff + m * 2048 + k * 1024); } while (0)
; #define PG8_LDB(dst, b, h) do { _Pragma("unroll") for (int n = 0; n < 2; ++n) _Pragma("unroll") for (int k = 0; k < 2; ++k) dst[n][k] = *(const PG8_LAS bf16x8*)(lds + PG8_SB(b, h) + boff + n * 2048 + k * 1024); } while (0)
; #define PG8_MMA(ai, bj, At, Bt) do { __builtin_amdgcn_s_setprio(1); _Pragma("unroll") for (int m = 0; m < 4; ++m) _Pragma("unroll") for (int n = 0; n < 2; ++n) _Pragma("unroll") for (int k = 0; k < 2; ++k) \
;         acc[ai][bj][m][n] = __builtin_amdgcn_mfma_f32_16x16x32_bf16(Bt[n][k], At[m][k], acc[ai][bj][m][n], 0, 0, 0); __builtin_amdgcn_s_setprio(0); } while (0)
; #define PG8_WAIT_V(n) asm volatile("s_waitcnt vmcnt(" #n ")" ::: "memory")
; #define PG8_WAIT_L(n) asm volatile("s_waitcnt lgkmcnt(" #n ")" ::: "memory")
; #define PG8_BAR __builtin_amdgcn_s_barrier()
; #define PG8_SCHED __builtin_amdgcn_sched_barrier(0)
; template <class Epi, class Sched, bool ALIGN_EPI = false, bool SP2 = false>
; __device__ __forceinline__ void gemm_phase(PG8_LAS unsigned char* lds, const Gemm g, const Sched S, const Epi E) {
;     ...
;             PG8_LDB(B0, 0, 0); PG8_LDB(B1, 0, 1); PG8_SCHED; PG8_LDA(At, 0, 0); PG8_STAGE(PG8_SA(1, 1), a1 + hstep, voffA);
;             PG8_WAIT_V(8); PG8_WAIT_L(0); PG8_BAR; PG8_MMA(0, 0, At, B0); PG8_MMA(0, 1, At, B1); PG8_BAR; PG8_SCHED;
;             PG8_LDA(At, 0, 1); PG8_STAGE(PG8_SB(0, 0), b2, voffB); PG8_STAGE(PG8_SB(0, 1), b2 + hstep, voffB); PG8_STAGE(PG8_SA(0, 0), a2, voffA);
;             PG8_WAIT_V(8); PG8_WAIT_L(0); PG8_BAR; PG8_MMA(1, 0, At, B0); PG8_MMA(1, 1, At, B1); PG8_BAR; PG8_SCHED;
.LBB0_180:
	v_add_u32_e32 v140, 0x10000, v143
	ds_read_b128 v[154:157], v140
	ds_read_b128 v[158:161], v140 offset:1024
	ds_read_b128 v[162:165], v140 offset:2048
	ds_read_b128 v[166:169], v140 offset:3072
	v_add_u32_e32 v140, 0x14000, v143
	ds_read_b128 v[170:173], v140
	ds_read_b128 v[174:177], v140 offset:1024
	ds_read_b128 v[182:185], v140 offset:2048
	ds_read_b128 v[198:201], v140 offset:3072
	s_add_i32 s20, s18, 2
	s_add_u32 s21, s16, 0x80
	s_addc_u32 s19, s17, 0
	s_add_i32 s25, 0, 0x10000
	s_cmp_eq_u32 s75, s18
	s_cselect_b32 s19, s1, s19
	s_cselect_b32 s18, s0, s21
	s_cselect_b32 s23, s59, s15
	s_cselect_b32 s22, s58, s14
	s_add_i32 s21, 0, 0x14000
	v_lshl_add_u64 v[140:141], s[16:17], 0, v[136:137]
	s_add_i32 m0, s68, 0xc000
	ds_read_b128 v[202:205], v146
	ds_read_b128 v[206:209], v146 offset:1024
	ds_read_b128 v[210:213], v146 offset:2048
	ds_read_b128 v[214:217], v146 offset:3072
	ds_read_b128 v[218:221], v146 offset:4096
	ds_read_b128 v[222:225], v146 offset:5120
	ds_read_b128 v[226:229], v146 offset:6144
	ds_read_b128 v[230:233], v146 offset:7168
	global_load_lds_dwordx4 v[140:141], off
	v_lshl_add_u64 v[140:141], s[16:17], 0, v[138:139]
	s_add_i32 m0, s68, 0xe000
	s_nop 0
	global_load_lds_dwordx4 v[140:141], off
	s_waitcnt vmcnt(8) lgkmcnt(0)
	s_barrier
	s_setprio 1
	v_mfma_f32_16x16x32_bf16 v[126:129], v[154:157], v[202:205], v[126:129]
	v_mfma_f32_16x16x32_bf16 v[118:121], v[162:165], v[202:205], v[118:121]
	v_mfma_f32_16x16x32_bf16 v[110:113], v[154:157], v[210:213], v[110:113]
	v_mfma_f32_16x16x32_bf16 v[102:105], v[162:165], v[210:213], v[102:105]
	v_mfma_f32_16x16x32_bf16 v[94:97], v[154:157], v[218:221], v[94:97]
	v_mfma_f32_16x16x32_bf16 v[86:89], v[162:165], v[218:221], v[86:89]
	v_mfma_f32_16x16x32_bf16 v[78:81], v[154:157], v[226:229], v[78:81]
	v_mfma_f32_16x16x32_bf16 v[70:73], v[162:165], v[226:229], v[70:73]
	v_mfma_f32_16x16x32_bf16 v[126:129], v[158:161], v[206:209], v[126:129]
	v_mfma_f32_16x16x32_bf16 v[118:121], v[166:169], v[206:209], v[118:121]
	v_mfma_f32_16x16x32_bf16 v[110:113], v[158:161], v[214:217], v[110:113]
	v_mfma_f32_16x16x32_bf16 v[102:105], v[166:169], v[214:217], v[102:105]
	v_mfma_f32_16x16x32_bf16 v[94:97], v[158:161], v[222:225], v[94:97]
	v_mfma_f32_16x16x32_bf16 v[86:89], v[166:169], v[222:225], v[86:89]
	v_mfma_f32_16x16x32_bf16 v[78:81], v[158:161], v[230:233], v[78:81]
	v_mfma_f32_16x16x32_bf16 v[70:73], v[166:169], v[230:233], v[70:73]
	s_setprio 0
	s_setprio 1
	v_mfma_f32_16x16x32_bf16 v[122:125], v[170:173], v[202:205], v[122:125]
	v_mfma_f32_16x16x32_bf16 v[114:117], v[182:185], v[202:205], v[114:117]
	v_mfma_f32_16x16x32_bf16 v[106:109], v[170:173], v[210:213], v[106:109]
	v_mfma_f32_16x16x32_bf16 v[98:101], v[182:185], v[210:213], v[98:101]
	v_mfma_f32_16x16x32_bf16 v[90:93], v[170:173], v[218:221], v[90:93]
	v_mfma_f32_16x16x32_bf16 v[82:85], v[182:185], v[218:221], v[82:85]
	v_mfma_f32_16x16x32_bf16 v[74:77], v[170:173], v[226:229], v[74:77]
	v_mfma_f32_16x16x32_bf16 v[66:69], v[182:185], v[226:229], v[66:69]
	v_mfma_f32_16x16x32_bf16 v[122:125], v[174:177], v[206:209], v[122:125]
	v_mfma_f32_16x16x32_bf16 v[114:117], v[198:201], v[206:209], v[114:117]
	v_mfma_f32_16x16x32_bf16 v[106:109], v[174:177], v[214:217], v[106:109]
	v_mfma_f32_16x16x32_bf16 v[98:101], v[198:201], v[214:217], v[98:101]
	v_mfma_f32_16x16x32_bf16 v[90:93], v[174:177], v[222:225], v[90:93]
	v_mfma_f32_16x16x32_bf16 v[82:85], v[198:201], v[222:225], v[82:85]
	v_mfma_f32_16x16x32_bf16 v[74:77], v[174:177], v[230:233], v[74:77]
	v_mfma_f32_16x16x32_bf16 v[66:69], v[198:201], v[230:233], v[66:69]
	s_setprio 0
	s_barrier
	s_add_i32 s25, s25, s61
	v_lshl_add_u64 v[140:141], s[22:23], 0, v[0:1]
	s_mov_b32 m0, s25
	ds_read_b128 v[202:205], v146 offset:16384
	ds_read_b128 v[206:209], v146 offset:17408
	ds_read_b128 v[210:213], v146 offset:18432
	ds_read_b128 v[214:217], v146 offset:19456
	ds_read_b128 v[218:221], v146 offset:20480
	ds_read_b128 v[222:225], v146 offset:21504
	ds_read_b128 v[226:229], v146 offset:22528
	ds_read_b128 v[230:233], v146 offset:23552
	global_load_lds_dwordx4 v[140:141], off
	s_add_i32 m0, s25, 0x2000
	v_lshl_add_u64 v[234:235], s[22:23], 0, v[130:131]
	s_add_u32 s22, s22, s28
	s_addc_u32 s23, s23, 0
	s_add_i32 s21, s21, s61
	global_load_lds_dwordx4 v[234:235], off
	v_lshl_add_u64 v[236:237], s[22:23], 0, v[0:1]
	s_mov_b32 m0, s21
	v_lshl_add_u64 v[238:239], s[22:23], 0, v[130:131]
	global_load_lds_dwordx4 v[236:237], off
	s_add_i32 m0, s21, 0x2000
	v_lshl_add_u64 v[240:241], s[18:19], 0, v[134:135]
	global_load_lds_dwordx4 v[238:239], off
	s_mov_b32 m0, s68
	v_lshl_add_u64 v[242:243], s[18:19], 0, v[132:133]
	global_load_lds_dwordx4 v[240:241], off
	s_mov_b32 m0, s69
	s_nop 0
	global_load_lds_dwordx4 v[242:243], off
	s_waitcnt vmcnt(8) lgkmcnt(0)
	s_barrier
; #define PG8_STAGE(bufoff, gbase, voff) do { _Pragma("unroll") for (int _i = 0; _i < 2; ++_i) \
;         __builtin_amdgcn_global_load_lds((const unsigned*)((const char*)(gbase) + (voff)[_i]), (PG8_LAS unsigned*)(lds + (bufoff) + ldsw + _i * 8192), 16, 0, 0); } while (0)
; #define PG8_LDA(dst, b, h) do { _Pragma("unroll") for (int m = 0; m < 4; ++m) _Pragma("unroll") for (int k = 0; k < 2; ++k) dst[m][k] = *(const PG8_LAS bf16x8*)(lds + PG8_SA(b, h) + aoff + m * 2048 + k * 1024); } while (0)
; #define PG8_LDB(dst, b, h) do { _Pragma("unroll") for (int n = 0; n < 2; ++n) _Pragma("unroll") for (int k = 0; k < 2; ++k) dst[n][k] = *(const PG8_LAS bf16x8*)(lds + PG8_SB(b, h) + boff + n * 2048 + k * 1024); } while (0)
; #define PG8_MMA(ai, bj, At, Bt) do { __builtin_amdgcn_s_setprio(1); _Pragma("unroll") for (int m = 0; m < 4; ++m) _Pragma("unroll") for (int n = 0; n < 2; ++n) _Pragma("unroll") for (int k = 0; k < 2; ++k) \
;         acc[ai][bj][m][n] = __builtin_amdgcn_mfma_f32_16x16x32_bf16(Bt[n][k], At[m][k], acc[ai][bj][m][n], 0, 0, 0); __builtin_amdgcn_s_setprio(0); } while (0)
; #define PG8_WAIT_V(n) asm volatile("s_waitcnt vmcnt(" #n ")" ::: "memory")
; #define PG8_WAIT_L(n) asm volatile("s_waitcnt lgkmcnt(" #n ")" ::: "memory")
; #define PG8_BAR __builtin_amdgcn_s_barrier()
; #define PG8_SCHED __builtin_amdgcn_sched_barrier(0)
; template <class Epi, class Sched, bool ALIGN_EPI = false, bool SP2 = false>
; __device__ __forceinline__ void gemm_phase(PG8_LAS unsigned char* lds, const Gemm g, const Sched S, const Epi E) {
;     ...
;             PG8_WAIT_V(8); PG8_WAIT_L(0); PG8_BAR; PG8_MMA(1, 0, At, B0); PG8_MMA(1, 1, At, B1); PG8_BAR; PG8_SCHED;
;             PG8_LDB(B0, 1, 0); PG8_LDB(B1, 1, 1); PG8_SCHED; PG8_LDA(At, 1, 0); PG8_STAGE(PG8_SA(0, 1), a2 + hstep, voffA);
;             PG8_WAIT_V(8); PG8_WAIT_L(0); PG8_BAR; PG8_MMA(0, 0, At, B0); PG8_MMA(0, 1, At, B1); PG8_BAR; PG8_SCHED;
	s_setprio 1
	v_mfma_f32_16x16x32_bf16 v[62:65], v[154:157], v[202:205], v[62:65]
	v_mfma_f32_16x16x32_bf16 v[54:57], v[162:165], v[202:205], v[54:57]
	v_mfma_f32_16x16x32_bf16 v[46:49], v[154:157], v[210:213], v[46:49]
	v_mfma_f32_16x16x32_bf16 v[38:41], v[162:165], v[210:213], v[38:41]
	v_mfma_f32_16x16x32_bf16 v[30:33], v[154:157], v[218:221], v[30:33]
	v_mfma_f32_16x16x32_bf16 v[22:25], v[162:165], v[218:221], v[22:25]
	v_mfma_f32_16x16x32_bf16 v[14:17], v[154:157], v[226:229], v[14:17]
	v_mfma_f32_16x16x32_bf16 v[6:9], v[162:165], v[226:229], v[6:9]
	v_mfma_f32_16x16x32_bf16 v[62:65], v[158:161], v[206:209], v[62:65]
	v_mfma_f32_16x16x32_bf16 v[54:57], v[166:169], v[206:209], v[54:57]
	v_mfma_f32_16x16x32_bf16 v[46:49], v[158:161], v[214:217], v[46:49]
	v_mfma_f32_16x16x32_bf16 v[38:41], v[166:169], v[214:217], v[38:41]
	v_mfma_f32_16x16x32_bf16 v[30:33], v[158:161], v[222:225], v[30:33]
	v_mfma_f32_16x16x32_bf16 v[22:25], v[166:169], v[222:225], v[22:25]
	v_mfma_f32_16x16x32_bf16 v[14:17], v[158:161], v[230:233], v[14:17]
	v_mfma_f32_16x16x32_bf16 v[6:9], v[166:169], v[230:233], v[6:9]
	s_setprio 0
	s_setprio 1
	v_mfma_f32_16x16x32_bf16 v[58:61], v[170:173], v[202:205], v[58:61]
	v_mfma_f32_16x16x32_bf16 v[50:53], v[182:185], v[202:205], v[50:53]
	v_mfma_f32_16x16x32_bf16 v[42:45], v[170:173], v[210:213], v[42:45]
	v_mfma_f32_16x16x32_bf16 v[34:37], v[182:185], v[210:213], v[34:37]
	v_mfma_f32_16x16x32_bf16 v[26:29], v[170:173], v[218:221], v[26:29]
	v_mfma_f32_16x16x32_bf16 v[18:21], v[182:185], v[218:221], v[18:21]
	v_mfma_f32_16x16x32_bf16 v[10:13], v[170:173], v[226:229], v[10:13]
	v_mfma_f32_16x16x32_bf16 v[2:5], v[182:185], v[226:229], v[2:5]
	v_mfma_f32_16x16x32_bf16 v[58:61], v[174:177], v[206:209], v[58:61]
	v_mfma_f32_16x16x32_bf16 v[50:53], v[198:201], v[206:209], v[50:53]
	v_mfma_f32_16x16x32_bf16 v[42:45], v[174:177], v[214:217], v[42:45]
	v_mfma_f32_16x16x32_bf16 v[34:37], v[198:201], v[214:217], v[34:37]
	v_mfma_f32_16x16x32_bf16 v[26:29], v[174:177], v[222:225], v[26:29]
	v_mfma_f32_16x16x32_bf16 v[18:21], v[198:201], v[222:225], v[18:21]
	v_mfma_f32_16x16x32_bf16 v[10:13], v[174:177], v[230:233], v[10:13]
	v_mfma_f32_16x16x32_bf16 v[2:5], v[198:201], v[230:233], v[2:5]
	s_setprio 0
	s_barrier
	v_add_u32_e32 v166, 0x18000, v143
	v_add_u32_e32 v186, 0x1c000, v143
	ds_read_b128 v[154:157], v166
	ds_read_b128 v[158:161], v166 offset:1024
	ds_read_b128 v[162:165], v166 offset:2048
	ds_read_b128 v[166:169], v166 offset:3072
	ds_read_b128 v[170:173], v186
	ds_read_b128 v[174:177], v186 offset:1024
	ds_read_b128 v[182:185], v186 offset:2048
	ds_read_b128 v[198:201], v186 offset:3072
	s_add_i32 s21, 0, 0x18000
	s_add_i32 s22, 0, 0x1c000
	s_add_u32 s18, s18, s28
	s_addc_u32 s19, s19, 0
	s_mov_b32 m0, s70
	v_lshl_add_u64 v[244:245], s[18:19], 0, v[134:135]
	ds_read_b128 v[202:205], v146 offset:32768
	ds_read_b128 v[206:209], v146 offset:33792
	ds_read_b128 v[210:213], v146 offset:34816
	ds_read_b128 v[214:217], v146 offset:35840
	ds_read_b128 v[218:221], v146 offset:36864
	ds_read_b128 v[222:225], v146 offset:37888
	ds_read_b128 v[226:229], v146 offset:38912
	ds_read_b128 v[230:233], v146 offset:39936
	global_load_lds_dwordx4 v[244:245], off
	v_lshl_add_u64 v[244:245], s[18:19], 0, v[132:133]
	s_mov_b32 m0, s71
	s_nop 0
	global_load_lds_dwordx4 v[244:245], off
	s_waitcnt vmcnt(8) lgkmcnt(0)
	s_barrier
	s_setprio 1
	v_mfma_f32_16x16x32_bf16 v[126:129], v[154:157], v[202:205], v[126:129]
	v_mfma_f32_16x16x32_bf16 v[118:121], v[162:165], v[202:205], v[118:121]
	v_mfma_f32_16x16x32_bf16 v[110:113], v[154:157], v[210:213], v[110:113]
	v_mfma_f32_16x16x32_bf16 v[102:105], v[162:165], v[210:213], v[102:105]
	v_mfma_f32_16x16x32_bf16 v[94:97], v[154:157], v[218:221], v[94:97]
	v_mfma_f32_16x16x32_bf16 v[86:89], v[162:165], v[218:221], v[86:89]
	v_mfma_f32_16x16x32_bf16 v[78:81], v[154:157], v[226:229], v[78:81]
	v_mfma_f32_16x16x32_bf16 v[70:73], v[162:165], v[226:229], v[70:73]
	v_mfma_f32_16x16x32_bf16 v[126:129], v[158:161], v[206:209], v[126:129]
	v_mfma_f32_16x16x32_bf16 v[118:121], v[166:169], v[206:209], v[118:121]
	v_mfma_f32_16x16x32_bf16 v[110:113], v[158:161], v[214:217], v[110:113]
	v_mfma_f32_16x16x32_bf16 v[102:105], v[166:169], v[214:217], v[102:105]
	v_mfma_f32_16x16x32_bf16 v[94:97], v[158:161], v[222:225], v[94:97]
	v_mfma_f32_16x16x32_bf16 v[86:89], v[166:169], v[222:225], v[86:89]
	v_mfma_f32_16x16x32_bf16 v[78:81], v[158:161], v[230:233], v[78:81]
	v_mfma_f32_16x16x32_bf16 v[70:73], v[166:169], v[230:233], v[70:73]
	s_setprio 0
	s_setprio 1
	v_mfma_f32_16x16x32_bf16 v[122:125], v[170:173], v[202:205], v[122:125]
	v_mfma_f32_16x16x32_bf16 v[114:117], v[182:185], v[202:205], v[114:117]
	v_mfma_f32_16x16x32_bf16 v[106:109], v[170:173], v[210:213], v[106:109]
	v_mfma_f32_16x16x32_bf16 v[98:101], v[182:185], v[210:213], v[98:101]
	v_mfma_f32_16x16x32_bf16 v[90:93], v[170:173], v[218:221], v[90:93]
	v_mfma_f32_16x16x32_bf16 v[82:85], v[182:185], v[218:221], v[82:85]
	v_mfma_f32_16x16x32_bf16 v[74:77], v[170:173], v[226:229], v[74:77]
	v_mfma_f32_16x16x32_bf16 v[66:69], v[182:185], v[226:229], v[66:69]
	v_mfma_f32_16x16x32_bf16 v[122:125], v[174:177], v[206:209], v[122:125]
	v_mfma_f32_16x16x32_bf16 v[114:117], v[198:201], v[206:209], v[114:117]
	v_mfma_f32_16x16x32_bf16 v[106:109], v[174:177], v[214:217], v[106:109]
	v_mfma_f32_16x16x32_bf16 v[98:101], v[198:201], v[214:217], v[98:101]
	v_mfma_f32_16x16x32_bf16 v[90:93], v[174:177], v[222:225], v[90:93]
	v_mfma_f32_16x16x32_bf16 v[82:85], v[198:201], v[222:225], v[82:85]
	v_mfma_f32_16x16x32_bf16 v[74:77], v[174:177], v[230:233], v[74:77]
	v_mfma_f32_16x16x32_bf16 v[66:69], v[198:201], v[230:233], v[66:69]
	s_setprio 0
	s_barrier
; #define PG8_STAGE(bufoff, gbase, voff) do { _Pragma("unroll") for (int _i = 0; _i < 2; ++_i) \
;         __builtin_amdgcn_global_load_lds((const unsigned*)((const char*)(gbase) + (voff)[_i]), (PG8_LAS unsigned*)(lds + (bufoff) + ldsw + _i * 8192), 16, 0, 0); } while (0)
; #define PG8_LDA(dst, b, h) do { _Pragma("unroll") for (int m = 0; m < 4; ++m) _Pragma("unroll") for (int k = 0; k < 2; ++k) dst[m][k] = *(const PG8_LAS bf16x8*)(lds + PG8_SA(b, h) + aoff + m * 2048 + k * 1024); } while (0)
; #define PG8_MMA(ai, bj, At, Bt) do { __builtin_amdgcn_s_setprio(1); _Pragma("unroll") for (int m = 0; m < 4; ++m) _Pragma("unroll") for (int n = 0; n < 2; ++n) _Pragma("unroll") for (int k = 0; k < 2; ++k) \
;         acc[ai][bj][m][n] = __builtin_amdgcn_mfma_f32_16x16x32_bf16(Bt[n][k], At[m][k], acc[ai][bj][m][n], 0, 0, 0); __builtin_amdgcn_s_setprio(0); } while (0)
; #define PG8_WAIT_V(n) asm volatile("s_waitcnt vmcnt(" #n ")" ::: "memory")
; #define PG8_WAIT_L(n) asm volatile("s_waitcnt lgkmcnt(" #n ")" ::: "memory")
; #define PG8_BAR __builtin_amdgcn_s_barrier()
; #define PG8_SCHED __builtin_amdgcn_sched_barrier(0)
; template <class Epi, class Sched, bool ALIGN_EPI = false, bool SP2 = false>
; __device__ __forceinline__ void gemm_phase(PG8_LAS unsigned char* lds, const Gemm g, const Sched S, const Epi E) {
;     ...
;             PG8_LDA(At, 1, 1); PG8_STAGE(PG8_SB(1, 0), b3, voffB); PG8_STAGE(PG8_SB(1, 1), b3 + hstep, voffB); PG8_STAGE(PG8_SA(1, 0), a3, voffA);
;             PG8_WAIT_V(8); PG8_WAIT_L(0); PG8_BAR; PG8_MMA(1, 0, At, B0); PG8_MMA(1, 1, At, B1); PG8_BAR; PG8_SCHED;
	s_add_i32 s18, s21, s61
	v_lshl_add_u64 v[140:141], v[140:141], 0, s[12:13]
	s_mov_b32 m0, s18
	ds_read_b128 v[202:205], v146 offset:49152
	ds_read_b128 v[206:209], v146 offset:50176
	ds_read_b128 v[210:213], v146 offset:51200
	ds_read_b128 v[214:217], v146 offset:52224
	ds_read_b128 v[218:221], v146 offset:53248
	ds_read_b128 v[222:225], v146 offset:54272
	ds_read_b128 v[226:229], v146 offset:55296
	ds_read_b128 v[230:233], v146 offset:56320
	global_load_lds_dwordx4 v[140:141], off
	v_lshl_add_u64 v[140:141], v[234:235], 0, s[12:13]
	s_add_i32 m0, s18, 0x2000
	s_add_i32 s18, s22, s61
	global_load_lds_dwordx4 v[140:141], off
	v_lshl_add_u64 v[140:141], v[236:237], 0, s[12:13]
	s_mov_b32 m0, s18
	s_nop 0
	global_load_lds_dwordx4 v[140:141], off
	v_lshl_add_u64 v[140:141], v[238:239], 0, s[12:13]
	s_add_i32 m0, s18, 0x2000
	s_nop 0
	global_load_lds_dwordx4 v[140:141], off
	v_lshl_add_u64 v[140:141], v[240:241], 0, s[12:13]
	s_mov_b32 m0, s73
	s_nop 0
	global_load_lds_dwordx4 v[140:141], off
	v_lshl_add_u64 v[140:141], v[242:243], 0, s[12:13]
	s_mov_b32 m0, s74
	s_nop 0
	global_load_lds_dwordx4 v[140:141], off
	s_waitcnt vmcnt(8) lgkmcnt(0)
	s_barrier
	s_setprio 1
	v_mfma_f32_16x16x32_bf16 v[62:65], v[154:157], v[202:205], v[62:65]
	v_mfma_f32_16x16x32_bf16 v[54:57], v[162:165], v[202:205], v[54:57]
	v_mfma_f32_16x16x32_bf16 v[46:49], v[154:157], v[210:213], v[46:49]
	v_mfma_f32_16x16x32_bf16 v[38:41], v[162:165], v[210:213], v[38:41]
	v_mfma_f32_16x16x32_bf16 v[30:33], v[154:157], v[218:221], v[30:33]
	v_mfma_f32_16x16x32_bf16 v[22:25], v[162:165], v[218:221], v[22:25]
	v_mfma_f32_16x16x32_bf16 v[14:17], v[154:157], v[226:229], v[14:17]
	v_mfma_f32_16x16x32_bf16 v[6:9], v[162:165], v[226:229], v[6:9]
	v_mfma_f32_16x16x32_bf16 v[62:65], v[158:161], v[206:209], v[62:65]
	v_mfma_f32_16x16x32_bf16 v[54:57], v[166:169], v[206:209], v[54:57]
	v_mfma_f32_16x16x32_bf16 v[46:49], v[158:161], v[214:217], v[46:49]
	v_mfma_f32_16x16x32_bf16 v[38:41], v[166:169], v[214:217], v[38:41]
	v_mfma_f32_16x16x32_bf16 v[30:33], v[158:161], v[222:225], v[30:33]
	v_mfma_f32_16x16x32_bf16 v[22:25], v[166:169], v[222:225], v[22:25]
	v_mfma_f32_16x16x32_bf16 v[14:17], v[158:161], v[230:233], v[14:17]
	v_mfma_f32_16x16x32_bf16 v[6:9], v[166:169], v[230:233], v[6:9]
	s_setprio 0
	s_setprio 1
	v_mfma_f32_16x16x32_bf16 v[58:61], v[170:173], v[202:205], v[58:61]
	v_mfma_f32_16x16x32_bf16 v[50:53], v[182:185], v[202:205], v[50:53]
	v_mfma_f32_16x16x32_bf16 v[42:45], v[170:173], v[210:213], v[42:45]
	v_mfma_f32_16x16x32_bf16 v[34:37], v[182:185], v[210:213], v[34:37]
	v_mfma_f32_16x16x32_bf16 v[26:29], v[170:173], v[218:221], v[26:29]
	v_mfma_f32_16x16x32_bf16 v[18:21], v[182:185], v[218:221], v[18:21]
	v_mfma_f32_16x16x32_bf16 v[10:13], v[170:173], v[226:229], v[10:13]
	v_mfma_f32_16x16x32_bf16 v[2:5], v[182:185], v[226:229], v[2:5]
	v_mfma_f32_16x16x32_bf16 v[58:61], v[174:177], v[206:209], v[58:61]
	v_mfma_f32_16x16x32_bf16 v[50:53], v[198:201], v[206:209], v[50:53]
	v_mfma_f32_16x16x32_bf16 v[42:45], v[174:177], v[214:217], v[42:45]
	v_mfma_f32_16x16x32_bf16 v[34:37], v[198:201], v[214:217], v[34:37]
	v_mfma_f32_16x16x32_bf16 v[26:29], v[174:177], v[222:225], v[26:29]
	v_mfma_f32_16x16x32_bf16 v[18:21], v[198:201], v[222:225], v[18:21]
	v_mfma_f32_16x16x32_bf16 v[10:13], v[174:177], v[230:233], v[10:13]
	v_mfma_f32_16x16x32_bf16 v[2:5], v[198:201], v[230:233], v[2:5]
	s_setprio 0
	s_add_u32 s16, s16, 0x100
	s_addc_u32 s17, s17, 0
	s_add_u32 s14, s14, 0x100
	s_addc_u32 s15, s15, 0
	s_cmp_ge_u32 s20, s72
	s_mov_b32 s18, s20
	s_barrier
	s_cbranch_scc0 .LBB0_180
	s_and_b64 vcc, exec, s[56:57]
	s_cbranch_vccz .LBB0_183
	s_barrier

; #define PG8_STAGE(bufoff, gbase, voff) do { _Pragma("unroll") for (int _i = 0; _i < 2; ++_i) \
;         __builtin_amdgcn_global_load_lds((const unsigned*)((const char*)(gbase) + (voff)[_i]), (PG8_LAS unsigned*)(lds + (bufoff) + ldsw + _i * 8192), 16, 0, 0); } while (0)
; #define PG8_LDA(dst, b, h) do { _Pragma("unroll") for (int m = 0; m < 4; ++m) _Pragma("unroll") for (int k = 0; k < 2; ++k) dst[m][k] = *(const PG8_LAS bf16x8*)(lds + PG8_SA(b, h) + aoff + m * 2048 + k * 1024); } while (0)
; #define PG8_LDB(dst, b, h) do { _Pragma("unroll") for (int n = 0; n < 2; ++n) _Pragma("unroll") for (int k = 0; k < 2; ++k) dst[n][k] = *(const PG8_LAS bf16x8*)(lds + PG8_SB(b, h) + boff + n * 2048 + k * 1024); } while (0)
; #define PG8_MMA(ai, bj, At, Bt) do { __builtin_amdgcn_s_setprio(1); _Pragma("unroll") for (int m = 0; m < 4; ++m) _Pragma("unroll") for (int n = 0; n < 2; ++n) _Pragma("unroll") for (int k = 0; k < 2; ++k) \
;         acc[ai][bj][m][n] = __builtin_amdgcn_mfma_f32_16x16x32_bf16(Bt[n][k], At[m][k], acc[ai][bj][m][n], 0, 0, 0); __builtin_amdgcn_s_setprio(0); } while (0)
; #define PG8_WAIT_V(n) asm volatile("s_waitcnt vmcnt(" #n ")" ::: "memory")
; #define PG8_WAIT_L(n) asm volatile("s_waitcnt lgkmcnt(" #n ")" ::: "memory")
; #define PG8_BAR __builtin_amdgcn_s_barrier()
; #define PG8_SCHED __builtin_amdgcn_sched_barrier(0)
; template <class Epi, class Sched, bool ALIGN_EPI = false, bool SP2 = false>
; __device__ __forceinline__ void gemm_phase(PG8_LAS unsigned char* lds, const Gemm g, const Sched S, const Epi E) {
;     ...
;             PG8_LDB(B0, 0, 0); PG8_LDB(B1, 0, 1); PG8_SCHED; PG8_LDA(At, 0, 0); PG8_STAGE(PG8_SA(1, 1), a1 + hstep, voffA);
;             PG8_WAIT_V(8); PG8_WAIT_L(0); PG8_BAR; PG8_MMA(0, 0, At, B0); PG8_MMA(0, 1, At, B1); PG8_BAR; PG8_SCHED;
;             PG8_LDA(At, 0, 1); PG8_STAGE(PG8_SB(0, 0), b2, voffB); PG8_STAGE(PG8_SB(0, 1), b2 + hstep, voffB); PG8_STAGE(PG8_SA(0, 0), a2, voffA);
;             PG8_WAIT_V(8); PG8_WAIT_L(0); PG8_BAR; PG8_MMA(1, 0, At, B0); PG8_MMA(1, 1, At, B1); PG8_BAR; PG8_SCHED;
.LBB0_224:
	v_add_u32_e32 v141, 0x10000, v147
	ds_read_b128 v[154:157], v141
	ds_read_b128 v[158:161], v141 offset:1024
	ds_read_b128 v[162:165], v141 offset:2048
	ds_read_b128 v[166:169], v141 offset:3072
	v_add_u32_e32 v141, 0x14000, v147
	ds_read_b128 v[170:173], v141
	ds_read_b128 v[174:177], v141 offset:1024
	ds_read_b128 v[182:185], v141 offset:2048
	ds_read_b128 v[198:201], v141 offset:3072
	s_add_i32 s21, s20, 2
	s_add_u32 s22, s30, 0x80
	s_addc_u32 s23, s31, 0
	s_add_i32 s26, 0, 0x10000
	s_cmp_eq_u32 s81, s20
	s_cselect_b32 s75, s1, s23
	s_cselect_b32 s74, s0, s22
	s_cselect_b32 s23, s19, s15
	s_cselect_b32 s22, s18, s14
	s_add_i32 s20, 0, 0x14000
	v_lshl_add_u64 v[234:235], s[30:31], 0, v[136:137]
	s_add_i32 m0, s85, 0xc000
	ds_read_b128 v[202:205], v152
	ds_read_b128 v[206:209], v152 offset:1024
	ds_read_b128 v[210:213], v152 offset:2048
	ds_read_b128 v[214:217], v152 offset:3072
	ds_read_b128 v[218:221], v152 offset:4096
	ds_read_b128 v[222:225], v152 offset:5120
	ds_read_b128 v[226:229], v152 offset:6144
	ds_read_b128 v[230:233], v152 offset:7168
	global_load_lds_dwordx4 v[234:235], off
	v_lshl_add_u64 v[234:235], s[30:31], 0, v[138:139]
	s_add_i32 m0, s85, 0xe000
	s_nop 0
	global_load_lds_dwordx4 v[234:235], off
	s_waitcnt vmcnt(8) lgkmcnt(0)
	s_barrier
	s_setprio 1
	v_mfma_f32_16x16x32_bf16 v[126:129], v[154:157], v[202:205], v[126:129]
	v_mfma_f32_16x16x32_bf16 v[122:125], v[162:165], v[202:205], v[122:125]
	v_mfma_f32_16x16x32_bf16 v[110:113], v[154:157], v[210:213], v[110:113]
	v_mfma_f32_16x16x32_bf16 v[106:109], v[162:165], v[210:213], v[106:109]
	v_mfma_f32_16x16x32_bf16 v[94:97], v[154:157], v[218:221], v[94:97]
	v_mfma_f32_16x16x32_bf16 v[90:93], v[162:165], v[218:221], v[90:93]
	v_mfma_f32_16x16x32_bf16 v[78:81], v[154:157], v[226:229], v[78:81]
	v_mfma_f32_16x16x32_bf16 v[74:77], v[162:165], v[226:229], v[74:77]
	v_mfma_f32_16x16x32_bf16 v[126:129], v[158:161], v[206:209], v[126:129]
	v_mfma_f32_16x16x32_bf16 v[122:125], v[166:169], v[206:209], v[122:125]
	v_mfma_f32_16x16x32_bf16 v[110:113], v[158:161], v[214:217], v[110:113]
	v_mfma_f32_16x16x32_bf16 v[106:109], v[166:169], v[214:217], v[106:109]
	v_mfma_f32_16x16x32_bf16 v[94:97], v[158:161], v[222:225], v[94:97]
	v_mfma_f32_16x16x32_bf16 v[90:93], v[166:169], v[222:225], v[90:93]
	v_mfma_f32_16x16x32_bf16 v[78:81], v[158:161], v[230:233], v[78:81]
	v_mfma_f32_16x16x32_bf16 v[74:77], v[166:169], v[230:233], v[74:77]
	s_setprio 0
	s_setprio 1
	v_mfma_f32_16x16x32_bf16 v[118:121], v[170:173], v[202:205], v[118:121]
	v_mfma_f32_16x16x32_bf16 v[114:117], v[182:185], v[202:205], v[114:117]
	v_mfma_f32_16x16x32_bf16 v[102:105], v[170:173], v[210:213], v[102:105]
	v_mfma_f32_16x16x32_bf16 v[98:101], v[182:185], v[210:213], v[98:101]
	v_mfma_f32_16x16x32_bf16 v[86:89], v[170:173], v[218:221], v[86:89]
	v_mfma_f32_16x16x32_bf16 v[82:85], v[182:185], v[218:221], v[82:85]
	v_mfma_f32_16x16x32_bf16 v[70:73], v[170:173], v[226:229], v[70:73]
	v_mfma_f32_16x16x32_bf16 v[66:69], v[182:185], v[226:229], v[66:69]
	v_mfma_f32_16x16x32_bf16 v[118:121], v[174:177], v[206:209], v[118:121]
	v_mfma_f32_16x16x32_bf16 v[114:117], v[198:201], v[206:209], v[114:117]
	v_mfma_f32_16x16x32_bf16 v[102:105], v[174:177], v[214:217], v[102:105]
	v_mfma_f32_16x16x32_bf16 v[98:101], v[198:201], v[214:217], v[98:101]
	v_mfma_f32_16x16x32_bf16 v[86:89], v[174:177], v[222:225], v[86:89]
	v_mfma_f32_16x16x32_bf16 v[82:85], v[198:201], v[222:225], v[82:85]
	v_mfma_f32_16x16x32_bf16 v[70:73], v[174:177], v[230:233], v[70:73]
	v_mfma_f32_16x16x32_bf16 v[66:69], v[198:201], v[230:233], v[66:69]
	s_setprio 0
	s_barrier
	s_add_i32 s26, s26, s84
	v_lshl_add_u64 v[234:235], s[22:23], 0, v[0:1]
	s_mov_b32 m0, s26
	ds_read_b128 v[202:205], v152 offset:16384
	ds_read_b128 v[206:209], v152 offset:17408
	ds_read_b128 v[210:213], v152 offset:18432
	ds_read_b128 v[214:217], v152 offset:19456
	ds_read_b128 v[218:221], v152 offset:20480
	ds_read_b128 v[222:225], v152 offset:21504
	ds_read_b128 v[226:229], v152 offset:22528
	ds_read_b128 v[230:233], v152 offset:23552
	global_load_lds_dwordx4 v[234:235], off
	s_add_i32 m0, s26, 0x2000
	v_lshl_add_u64 v[236:237], s[22:23], 0, v[134:135]
	s_add_u32 s22, s22, s52
	s_addc_u32 s23, s23, 0
	s_add_i32 s20, s20, s84
	global_load_lds_dwordx4 v[236:237], off
	v_lshl_add_u64 v[238:239], s[22:23], 0, v[0:1]
	s_mov_b32 m0, s20
	v_lshl_add_u64 v[240:241], s[22:23], 0, v[134:135]
	global_load_lds_dwordx4 v[238:239], off
	s_add_i32 m0, s20, 0x2000
	v_lshl_add_u64 v[242:243], s[74:75], 0, v[130:131]
	global_load_lds_dwordx4 v[240:241], off
	s_mov_b32 m0, s85
	v_lshl_add_u64 v[244:245], s[74:75], 0, v[132:133]
	global_load_lds_dwordx4 v[242:243], off
	s_mov_b32 m0, s86
	s_nop 0
	global_load_lds_dwordx4 v[244:245], off
	s_waitcnt vmcnt(8) lgkmcnt(0)
	s_barrier
; #define PG8_STAGE(bufoff, gbase, voff) do { _Pragma("unroll") for (int _i = 0; _i < 2; ++_i) \
;         __builtin_amdgcn_global_load_lds((const unsigned*)((const char*)(gbase) + (voff)[_i]), (PG8_LAS unsigned*)(lds + (bufoff) + ldsw + _i * 8192), 16, 0, 0); } while (0)
; #define PG8_LDA(dst, b, h) do { _Pragma("unroll") for (int m = 0; m < 4; ++m) _Pragma("unroll") for (int k = 0; k < 2; ++k) dst[m][k] = *(const PG8_LAS bf16x8*)(lds + PG8_SA(b, h) + aoff + m * 2048 + k * 1024); } while (0)
; #define PG8_LDB(dst, b, h) do { _Pragma("unroll") for (int n = 0; n < 2; ++n) _Pragma("unroll") for (int k = 0; k < 2; ++k) dst[n][k] = *(const PG8_LAS bf16x8*)(lds + PG8_SB(b, h) + boff + n * 2048 + k * 1024); } while (0)
; #define PG8_MMA(ai, bj, At, Bt) do { __builtin_amdgcn_s_setprio(1); _Pragma("unroll") for (int m = 0; m < 4; ++m) _Pragma("unroll") for (int n = 0; n < 2; ++n) _Pragma("unroll") for (int k = 0; k < 2; ++k) \
;         acc[ai][bj][m][n] = __builtin_amdgcn_mfma_f32_16x16x32_bf16(Bt[n][k], At[m][k], acc[ai][bj][m][n], 0, 0, 0); __builtin_amdgcn_s_setprio(0); } while (0)
; #define PG8_WAIT_V(n) asm volatile("s_waitcnt vmcnt(" #n ")" ::: "memory")
; #define PG8_WAIT_L(n) asm volatile("s_waitcnt lgkmcnt(" #n ")" ::: "memory")
; #define PG8_BAR __builtin_amdgcn_s_barrier()
; #define PG8_SCHED __builtin_amdgcn_sched_barrier(0)
; template <class Epi, class Sched, bool ALIGN_EPI = false, bool SP2 = false>
; __device__ __forceinline__ void gemm_phase(PG8_LAS unsigned char* lds, const Gemm g, const Sched S, const Epi E) {
;     ...
;             PG8_WAIT_V(8); PG8_WAIT_L(0); PG8_BAR; PG8_MMA(1, 0, At, B0); PG8_MMA(1, 1, At, B1); PG8_BAR; PG8_SCHED;
;             PG8_LDB(B0, 1, 0); PG8_LDB(B1, 1, 1); PG8_SCHED; PG8_LDA(At, 1, 0); PG8_STAGE(PG8_SA(0, 1), a2 + hstep, voffA);
;             PG8_WAIT_V(8); PG8_WAIT_L(0); PG8_BAR; PG8_MMA(0, 0, At, B0); PG8_MMA(0, 1, At, B1); PG8_BAR; PG8_SCHED;
	s_setprio 1
	v_mfma_f32_16x16x32_bf16 v[62:65], v[154:157], v[202:205], v[62:65]
	v_mfma_f32_16x16x32_bf16 v[58:61], v[162:165], v[202:205], v[58:61]
	v_mfma_f32_16x16x32_bf16 v[46:49], v[154:157], v[210:213], v[46:49]
	v_mfma_f32_16x16x32_bf16 v[42:45], v[162:165], v[210:213], v[42:45]
	v_mfma_f32_16x16x32_bf16 v[30:33], v[154:157], v[218:221], v[30:33]
	v_mfma_f32_16x16x32_bf16 v[26:29], v[162:165], v[218:221], v[26:29]
	v_mfma_f32_16x16x32_bf16 v[14:17], v[154:157], v[226:229], v[14:17]
	v_mfma_f32_16x16x32_bf16 v[10:13], v[162:165], v[226:229], v[10:13]
	v_mfma_f32_16x16x32_bf16 v[62:65], v[158:161], v[206:209], v[62:65]
	v_mfma_f32_16x16x32_bf16 v[58:61], v[166:169], v[206:209], v[58:61]
	v_mfma_f32_16x16x32_bf16 v[46:49], v[158:161], v[214:217], v[46:49]
	v_mfma_f32_16x16x32_bf16 v[42:45], v[166:169], v[214:217], v[42:45]
	v_mfma_f32_16x16x32_bf16 v[30:33], v[158:161], v[222:225], v[30:33]
	v_mfma_f32_16x16x32_bf16 v[26:29], v[166:169], v[222:225], v[26:29]
	v_mfma_f32_16x16x32_bf16 v[14:17], v[158:161], v[230:233], v[14:17]
	v_mfma_f32_16x16x32_bf16 v[10:13], v[166:169], v[230:233], v[10:13]
	s_setprio 0
	s_setprio 1
	v_mfma_f32_16x16x32_bf16 v[54:57], v[170:173], v[202:205], v[54:57]
	v_mfma_f32_16x16x32_bf16 v[50:53], v[182:185], v[202:205], v[50:53]
	v_mfma_f32_16x16x32_bf16 v[38:41], v[170:173], v[210:213], v[38:41]
	v_mfma_f32_16x16x32_bf16 v[34:37], v[182:185], v[210:213], v[34:37]
	v_mfma_f32_16x16x32_bf16 v[22:25], v[170:173], v[218:221], v[22:25]
	v_mfma_f32_16x16x32_bf16 v[18:21], v[182:185], v[218:221], v[18:21]
	v_mfma_f32_16x16x32_bf16 v[6:9], v[170:173], v[226:229], v[6:9]
	v_mfma_f32_16x16x32_bf16 v[2:5], v[182:185], v[226:229], v[2:5]
	v_mfma_f32_16x16x32_bf16 v[54:57], v[174:177], v[206:209], v[54:57]
	v_mfma_f32_16x16x32_bf16 v[50:53], v[198:201], v[206:209], v[50:53]
	v_mfma_f32_16x16x32_bf16 v[38:41], v[174:177], v[214:217], v[38:41]
	v_mfma_f32_16x16x32_bf16 v[34:37], v[198:201], v[214:217], v[34:37]
	v_mfma_f32_16x16x32_bf16 v[22:25], v[174:177], v[222:225], v[22:25]
	v_mfma_f32_16x16x32_bf16 v[18:21], v[198:201], v[222:225], v[18:21]
	v_mfma_f32_16x16x32_bf16 v[6:9], v[174:177], v[230:233], v[6:9]
	v_mfma_f32_16x16x32_bf16 v[2:5], v[198:201], v[230:233], v[2:5]
	s_setprio 0
	s_barrier
	v_add_u32_e32 v141, 0x18000, v147
	ds_read_b128 v[154:157], v141
	ds_read_b128 v[158:161], v141 offset:1024
	ds_read_b128 v[162:165], v141 offset:2048
	ds_read_b128 v[166:169], v141 offset:3072
	v_add_u32_e32 v141, 0x1c000, v147
	ds_read_b128 v[170:173], v141
	ds_read_b128 v[174:177], v141 offset:1024
	ds_read_b128 v[182:185], v141 offset:2048
	ds_read_b128 v[198:201], v141 offset:3072
	s_add_i32 s20, 0, 0x18000
	s_add_i32 s26, 0, 0x1c000
	s_add_u32 s22, s74, s52
	s_addc_u32 s23, s75, 0
	s_mov_b32 m0, s87
	v_lshl_add_u64 v[246:247], s[22:23], 0, v[130:131]
	ds_read_b128 v[202:205], v152 offset:32768
	ds_read_b128 v[206:209], v152 offset:33792
	ds_read_b128 v[210:213], v152 offset:34816
	ds_read_b128 v[214:217], v152 offset:35840
	ds_read_b128 v[218:221], v152 offset:36864
	ds_read_b128 v[222:225], v152 offset:37888
	ds_read_b128 v[226:229], v152 offset:38912
	ds_read_b128 v[230:233], v152 offset:39936
	global_load_lds_dwordx4 v[246:247], off
	v_lshl_add_u64 v[246:247], s[22:23], 0, v[132:133]
	s_mov_b32 m0, s88
	s_nop 0
	global_load_lds_dwordx4 v[246:247], off
	s_waitcnt vmcnt(8) lgkmcnt(0)
	s_barrier
	s_setprio 1
	v_mfma_f32_16x16x32_bf16 v[126:129], v[154:157], v[202:205], v[126:129]
	v_mfma_f32_16x16x32_bf16 v[122:125], v[162:165], v[202:205], v[122:125]
	v_mfma_f32_16x16x32_bf16 v[110:113], v[154:157], v[210:213], v[110:113]
	v_mfma_f32_16x16x32_bf16 v[106:109], v[162:165], v[210:213], v[106:109]
	v_mfma_f32_16x16x32_bf16 v[94:97], v[154:157], v[218:221], v[94:97]
	v_mfma_f32_16x16x32_bf16 v[90:93], v[162:165], v[218:221], v[90:93]
	v_mfma_f32_16x16x32_bf16 v[78:81], v[154:157], v[226:229], v[78:81]
	v_mfma_f32_16x16x32_bf16 v[74:77], v[162:165], v[226:229], v[74:77]
	v_mfma_f32_16x16x32_bf16 v[126:129], v[158:161], v[206:209], v[126:129]
	v_mfma_f32_16x16x32_bf16 v[122:125], v[166:169], v[206:209], v[122:125]
	v_mfma_f32_16x16x32_bf16 v[110:113], v[158:161], v[214:217], v[110:113]
	v_mfma_f32_16x16x32_bf16 v[106:109], v[166:169], v[214:217], v[106:109]
	v_mfma_f32_16x16x32_bf16 v[94:97], v[158:161], v[222:225], v[94:97]
	v_mfma_f32_16x16x32_bf16 v[90:93], v[166:169], v[222:225], v[90:93]
	v_mfma_f32_16x16x32_bf16 v[78:81], v[158:161], v[230:233], v[78:81]
	v_mfma_f32_16x16x32_bf16 v[74:77], v[166:169], v[230:233], v[74:77]
	s_setprio 0
	s_setprio 1
	v_mfma_f32_16x16x32_bf16 v[118:121], v[170:173], v[202:205], v[118:121]
	v_mfma_f32_16x16x32_bf16 v[114:117], v[182:185], v[202:205], v[114:117]
	v_mfma_f32_16x16x32_bf16 v[102:105], v[170:173], v[210:213], v[102:105]
	v_mfma_f32_16x16x32_bf16 v[98:101], v[182:185], v[210:213], v[98:101]
	v_mfma_f32_16x16x32_bf16 v[86:89], v[170:173], v[218:221], v[86:89]
	v_mfma_f32_16x16x32_bf16 v[82:85], v[182:185], v[218:221], v[82:85]
	v_mfma_f32_16x16x32_bf16 v[70:73], v[170:173], v[226:229], v[70:73]
	v_mfma_f32_16x16x32_bf16 v[66:69], v[182:185], v[226:229], v[66:69]
	v_mfma_f32_16x16x32_bf16 v[118:121], v[174:177], v[206:209], v[118:121]
	v_mfma_f32_16x16x32_bf16 v[114:117], v[198:201], v[206:209], v[114:117]
	v_mfma_f32_16x16x32_bf16 v[102:105], v[174:177], v[214:217], v[102:105]
	v_mfma_f32_16x16x32_bf16 v[98:101], v[198:201], v[214:217], v[98:101]
	v_mfma_f32_16x16x32_bf16 v[86:89], v[174:177], v[222:225], v[86:89]
	v_mfma_f32_16x16x32_bf16 v[82:85], v[198:201], v[222:225], v[82:85]
	v_mfma_f32_16x16x32_bf16 v[70:73], v[174:177], v[230:233], v[70:73]
	v_mfma_f32_16x16x32_bf16 v[66:69], v[198:201], v[230:233], v[66:69]
	s_setprio 0
	s_barrier
; #define PG8_STAGE(bufoff, gbase, voff) do { _Pragma("unroll") for (int _i = 0; _i < 2; ++_i) \
;         __builtin_amdgcn_global_load_lds((const unsigned*)((const char*)(gbase) + (voff)[_i]), (PG8_LAS unsigned*)(lds + (bufoff) + ldsw + _i * 8192), 16, 0, 0); } while (0)
; #define PG8_LDA(dst, b, h) do { _Pragma("unroll") for (int m = 0; m < 4; ++m) _Pragma("unroll") for (int k = 0; k < 2; ++k) dst[m][k] = *(const PG8_LAS bf16x8*)(lds + PG8_SA(b, h) + aoff + m * 2048 + k * 1024); } while (0)
; #define PG8_MMA(ai, bj, At, Bt) do { __builtin_amdgcn_s_setprio(1); _Pragma("unroll") for (int m = 0; m < 4; ++m) _Pragma("unroll") for (int n = 0; n < 2; ++n) _Pragma("unroll") for (int k = 0; k < 2; ++k) \
;         acc[ai][bj][m][n] = __builtin_amdgcn_mfma_f32_16x16x32_bf16(Bt[n][k], At[m][k], acc[ai][bj][m][n], 0, 0, 0); __builtin_amdgcn_s_setprio(0); } while (0)
; #define PG8_WAIT_V(n) asm volatile("s_waitcnt vmcnt(" #n ")" ::: "memory")
; #define PG8_WAIT_L(n) asm volatile("s_waitcnt lgkmcnt(" #n ")" ::: "memory")
; #define PG8_BAR __builtin_amdgcn_s_barrier()
; #define PG8_SCHED __builtin_amdgcn_sched_barrier(0)
; template <class Epi, class Sched, bool ALIGN_EPI = false, bool SP2 = false>
; __device__ __forceinline__ void gemm_phase(PG8_LAS unsigned char* lds, const Gemm g, const Sched S, const Epi E) {
;     ...
;             PG8_LDA(At, 1, 1); PG8_STAGE(PG8_SB(1, 0), b3, voffB); PG8_STAGE(PG8_SB(1, 1), b3 + hstep, voffB); PG8_STAGE(PG8_SA(1, 0), a3, voffA);
;             PG8_WAIT_V(8); PG8_WAIT_L(0); PG8_BAR; PG8_MMA(1, 0, At, B0); PG8_MMA(1, 1, At, B1); PG8_BAR; PG8_SCHED;
	s_add_i32 s20, s20, s84
	v_lshl_add_u64 v[234:235], v[234:235], 0, s[12:13]
	s_mov_b32 m0, s20
	ds_read_b128 v[202:205], v152 offset:49152
	ds_read_b128 v[206:209], v152 offset:50176
	ds_read_b128 v[210:213], v152 offset:51200
	ds_read_b128 v[214:217], v152 offset:52224
	ds_read_b128 v[218:221], v152 offset:53248
	ds_read_b128 v[222:225], v152 offset:54272
	ds_read_b128 v[226:229], v152 offset:55296
	ds_read_b128 v[230:233], v152 offset:56320
	global_load_lds_dwordx4 v[234:235], off
	v_lshl_add_u64 v[234:235], v[236:237], 0, s[12:13]
	s_add_i32 m0, s20, 0x2000
	s_add_i32 s20, s26, s84
	global_load_lds_dwordx4 v[234:235], off
	v_lshl_add_u64 v[234:235], v[238:239], 0, s[12:13]
	s_mov_b32 m0, s20
	s_nop 0
	global_load_lds_dwordx4 v[234:235], off
	v_lshl_add_u64 v[234:235], v[240:241], 0, s[12:13]
	s_add_i32 m0, s20, 0x2000
	s_nop 0
	global_load_lds_dwordx4 v[234:235], off
	v_lshl_add_u64 v[234:235], v[242:243], 0, s[12:13]
	s_mov_b32 m0, s3
	s_nop 0
	global_load_lds_dwordx4 v[234:235], off
	v_lshl_add_u64 v[234:235], v[244:245], 0, s[12:13]
	s_mov_b32 m0, s24
	s_nop 0
	global_load_lds_dwordx4 v[234:235], off
	s_waitcnt vmcnt(8) lgkmcnt(0)
	s_barrier
	s_setprio 1
	v_mfma_f32_16x16x32_bf16 v[62:65], v[154:157], v[202:205], v[62:65]
	v_mfma_f32_16x16x32_bf16 v[58:61], v[162:165], v[202:205], v[58:61]
	v_mfma_f32_16x16x32_bf16 v[46:49], v[154:157], v[210:213], v[46:49]
	v_mfma_f32_16x16x32_bf16 v[42:45], v[162:165], v[210:213], v[42:45]
	v_mfma_f32_16x16x32_bf16 v[30:33], v[154:157], v[218:221], v[30:33]
	v_mfma_f32_16x16x32_bf16 v[26:29], v[162:165], v[218:221], v[26:29]
	v_mfma_f32_16x16x32_bf16 v[14:17], v[154:157], v[226:229], v[14:17]
	v_mfma_f32_16x16x32_bf16 v[10:13], v[162:165], v[226:229], v[10:13]
	v_mfma_f32_16x16x32_bf16 v[62:65], v[158:161], v[206:209], v[62:65]
	v_mfma_f32_16x16x32_bf16 v[58:61], v[166:169], v[206:209], v[58:61]
	v_mfma_f32_16x16x32_bf16 v[46:49], v[158:161], v[214:217], v[46:49]
	v_mfma_f32_16x16x32_bf16 v[42:45], v[166:169], v[214:217], v[42:45]
	v_mfma_f32_16x16x32_bf16 v[30:33], v[158:161], v[222:225], v[30:33]
	v_mfma_f32_16x16x32_bf16 v[26:29], v[166:169], v[222:225], v[26:29]
	v_mfma_f32_16x16x32_bf16 v[14:17], v[158:161], v[230:233], v[14:17]
	v_mfma_f32_16x16x32_bf16 v[10:13], v[166:169], v[230:233], v[10:13]
	s_setprio 0
	s_setprio 1
	v_mfma_f32_16x16x32_bf16 v[54:57], v[170:173], v[202:205], v[54:57]
	v_mfma_f32_16x16x32_bf16 v[50:53], v[182:185], v[202:205], v[50:53]
	v_mfma_f32_16x16x32_bf16 v[38:41], v[170:173], v[210:213], v[38:41]
	v_mfma_f32_16x16x32_bf16 v[34:37], v[182:185], v[210:213], v[34:37]
	v_mfma_f32_16x16x32_bf16 v[22:25], v[170:173], v[218:221], v[22:25]
	v_mfma_f32_16x16x32_bf16 v[18:21], v[182:185], v[218:221], v[18:21]
	v_mfma_f32_16x16x32_bf16 v[6:9], v[170:173], v[226:229], v[6:9]
	v_mfma_f32_16x16x32_bf16 v[2:5], v[182:185], v[226:229], v[2:5]
	v_mfma_f32_16x16x32_bf16 v[54:57], v[174:177], v[206:209], v[54:57]
	v_mfma_f32_16x16x32_bf16 v[50:53], v[198:201], v[206:209], v[50:53]
	v_mfma_f32_16x16x32_bf16 v[38:41], v[174:177], v[214:217], v[38:41]
	v_mfma_f32_16x16x32_bf16 v[34:37], v[198:201], v[214:217], v[34:37]
	v_mfma_f32_16x16x32_bf16 v[22:25], v[174:177], v[222:225], v[22:25]
	v_mfma_f32_16x16x32_bf16 v[18:21], v[198:201], v[222:225], v[18:21]
	v_mfma_f32_16x16x32_bf16 v[6:9], v[174:177], v[230:233], v[6:9]
	v_mfma_f32_16x16x32_bf16 v[2:5], v[198:201], v[230:233], v[2:5]
	s_setprio 0
	s_add_u32 s30, s30, 0x100
	s_addc_u32 s31, s31, 0
	s_add_u32 s14, s14, 0x100
	s_addc_u32 s15, s15, 0
	s_cmp_ge_u32 s21, s80
	s_mov_b32 s20, s21
	s_barrier
	s_cbranch_scc0 .LBB0_224
	s_and_b64 vcc, exec, s[16:17]
	s_cbranch_vccz .LBB0_227
	s_barrier

; #define PG8_STAGE(bufoff, gbase, voff) do { _Pragma("unroll") for (int _i = 0; _i < 2; ++_i) \
;         __builtin_amdgcn_global_load_lds((const unsigned*)((const char*)(gbase) + (voff)[_i]), (PG8_LAS unsigned*)(lds + (bufoff) + ldsw + _i * 8192), 16, 0, 0); } while (0)
; #define PG8_LDA(dst, b, h) do { _Pragma("unroll") for (int m = 0; m < 4; ++m) _Pragma("unroll") for (int k = 0; k < 2; ++k) dst[m][k] = *(const PG8_LAS bf16x8*)(lds + PG8_SA(b, h) + aoff + m * 2048 + k * 1024); } while (0)
; #define PG8_LDB(dst, b, h) do { _Pragma("unroll") for (int n = 0; n < 2; ++n) _Pragma("unroll") for (int k = 0; k < 2; ++k) dst[n][k] = *(const PG8_LAS bf16x8*)(lds + PG8_SB(b, h) + boff + n * 2048 + k * 1024); } while (0)
; #define PG8_MMA(ai, bj, At, Bt) do { __builtin_amdgcn_s_setprio(1); _Pragma("unroll") for (int m = 0; m < 4; ++m) _Pragma("unroll") for (int n = 0; n < 2; ++n) _Pragma("unroll") for (int k = 0; k < 2; ++k) \
;         acc[ai][bj][m][n] = __builtin_amdgcn_mfma_f32_16x16x32_bf16(Bt[n][k], At[m][k], acc[ai][bj][m][n], 0, 0, 0); __builtin_amdgcn_s_setprio(0); } while (0)
; #define PG8_WAIT_V(n) asm volatile("s_waitcnt vmcnt(" #n ")" ::: "memory")
; #define PG8_WAIT_L(n) asm volatile("s_waitcnt lgkmcnt(" #n ")" ::: "memory")
; #define PG8_BAR __builtin_amdgcn_s_barrier()
; #define PG8_SCHED __builtin_amdgcn_sched_barrier(0)
; template <class Epi, class Sched, bool ALIGN_EPI = false, bool SP2 = false>
; __device__ __forceinline__ void gemm_phase(PG8_LAS unsigned char* lds, const Gemm g, const Sched S, const Epi E) {
;     ...
;             PG8_LDB(B0, 0, 0); PG8_LDB(B1, 0, 1); PG8_SCHED; PG8_LDA(At, 0, 0); PG8_STAGE(PG8_SA(1, 1), a1 + hstep, voffA);
;             PG8_WAIT_V(8); PG8_WAIT_L(0); PG8_BAR; PG8_MMA(0, 0, At, B0); PG8_MMA(0, 1, At, B1); PG8_BAR; PG8_SCHED;
;             PG8_LDA(At, 0, 1); PG8_STAGE(PG8_SB(0, 0), b2, voffB); PG8_STAGE(PG8_SB(0, 1), b2 + hstep, voffB); PG8_STAGE(PG8_SA(0, 0), a2, voffA);
;             PG8_WAIT_V(8); PG8_WAIT_L(0); PG8_BAR; PG8_MMA(1, 0, At, B0); PG8_MMA(1, 1, At, B1); PG8_BAR; PG8_SCHED;
.LBB0_416:
	v_add_u32_e32 v158, 0x10000, v168
	v_add_u32_e32 v171, 0x14000, v168
	ds_read_b128 v[134:137], v158
	ds_read_b128 v[138:141], v158 offset:1024
	ds_read_b128 v[142:145], v158 offset:2048
	ds_read_b128 v[158:161], v158 offset:3072
	ds_read_b128 v[162:165], v171
	ds_read_b128 v[172:175], v171 offset:1024
	ds_read_b128 v[182:185], v171 offset:2048
	ds_read_b128 v[198:201], v171 offset:3072
	s_add_i32 s3, s14, 2
	s_add_u32 s15, s68, s16
	s_addc_u32 s18, s69, s17
	s_add_u32 s20, s66, s16
	s_addc_u32 s21, s67, s17
	s_add_i32 s22, 0, 0x10000
	s_cmp_eq_u32 s89, s14
	s_cselect_b32 s19, s1, s18
	s_cselect_b32 s18, s0, s15
	s_cselect_b32 s15, s71, s21
	s_cselect_b32 s14, s70, s20
	s_add_i32 s20, 0, 0x14000
	v_lshl_add_u64 v[176:177], s[68:69], 0, v[132:133]
	s_add_i32 m0, s80, 0xc000
	ds_read_b128 v[202:205], v170
	ds_read_b128 v[206:209], v170 offset:1024
	ds_read_b128 v[210:213], v170 offset:2048
	ds_read_b128 v[214:217], v170 offset:3072
	ds_read_b128 v[218:221], v170 offset:4096
	ds_read_b128 v[222:225], v170 offset:5120
	ds_read_b128 v[226:229], v170 offset:6144
	ds_read_b128 v[230:233], v170 offset:7168
	global_load_lds_dwordx4 v[176:177], off
	v_lshl_add_u64 v[176:177], s[68:69], 0, v[130:131]
	s_add_i32 m0, s80, 0xe000
	s_nop 0
	global_load_lds_dwordx4 v[176:177], off
	s_waitcnt vmcnt(8) lgkmcnt(0)
	s_barrier
	s_setprio 1
	v_mfma_f32_16x16x32_bf16 v[58:61], v[134:137], v[202:205], v[58:61]
	v_mfma_f32_16x16x32_bf16 v[50:53], v[142:145], v[202:205], v[50:53]
	v_mfma_f32_16x16x32_bf16 v[14:17], v[134:137], v[210:213], v[14:17]
	v_mfma_f32_16x16x32_bf16 v[10:13], v[142:145], v[210:213], v[10:13]
	v_mfma_f32_16x16x32_bf16 v[30:33], v[134:137], v[218:221], v[30:33]
	v_mfma_f32_16x16x32_bf16 v[26:29], v[142:145], v[218:221], v[26:29]
	v_mfma_f32_16x16x32_bf16 v[46:49], v[134:137], v[226:229], v[46:49]
	v_mfma_f32_16x16x32_bf16 v[42:45], v[142:145], v[226:229], v[42:45]
	v_mfma_f32_16x16x32_bf16 v[58:61], v[138:141], v[206:209], v[58:61]
	v_mfma_f32_16x16x32_bf16 v[50:53], v[158:161], v[206:209], v[50:53]
	v_mfma_f32_16x16x32_bf16 v[14:17], v[138:141], v[214:217], v[14:17]
	v_mfma_f32_16x16x32_bf16 v[10:13], v[158:161], v[214:217], v[10:13]
	v_mfma_f32_16x16x32_bf16 v[30:33], v[138:141], v[222:225], v[30:33]
	v_mfma_f32_16x16x32_bf16 v[26:29], v[158:161], v[222:225], v[26:29]
	v_mfma_f32_16x16x32_bf16 v[46:49], v[138:141], v[230:233], v[46:49]
	v_mfma_f32_16x16x32_bf16 v[42:45], v[158:161], v[230:233], v[42:45]
	s_setprio 0
	s_setprio 1
	v_mfma_f32_16x16x32_bf16 v[6:9], v[162:165], v[202:205], v[6:9]
	v_mfma_f32_16x16x32_bf16 v[2:5], v[182:185], v[202:205], v[2:5]
	v_mfma_f32_16x16x32_bf16 v[22:25], v[162:165], v[210:213], v[22:25]
	v_mfma_f32_16x16x32_bf16 v[18:21], v[182:185], v[210:213], v[18:21]
	v_mfma_f32_16x16x32_bf16 v[38:41], v[162:165], v[218:221], v[38:41]
	v_mfma_f32_16x16x32_bf16 v[34:37], v[182:185], v[218:221], v[34:37]
	v_mfma_f32_16x16x32_bf16 v[62:65], v[162:165], v[226:229], v[62:65]
	v_mfma_f32_16x16x32_bf16 v[54:57], v[182:185], v[226:229], v[54:57]
	v_mfma_f32_16x16x32_bf16 v[6:9], v[172:175], v[206:209], v[6:9]
	v_mfma_f32_16x16x32_bf16 v[2:5], v[198:201], v[206:209], v[2:5]
	v_mfma_f32_16x16x32_bf16 v[22:25], v[172:175], v[214:217], v[22:25]
	v_mfma_f32_16x16x32_bf16 v[18:21], v[198:201], v[214:217], v[18:21]
	v_mfma_f32_16x16x32_bf16 v[38:41], v[172:175], v[222:225], v[38:41]
	v_mfma_f32_16x16x32_bf16 v[34:37], v[198:201], v[222:225], v[34:37]
	v_mfma_f32_16x16x32_bf16 v[62:65], v[172:175], v[230:233], v[62:65]
	v_mfma_f32_16x16x32_bf16 v[54:57], v[198:201], v[230:233], v[54:57]
	s_setprio 0
	s_barrier
	s_add_i32 s21, s22, s79
	v_lshl_add_u64 v[176:177], s[14:15], 0, v[148:149]
	s_mov_b32 m0, s21
	ds_read_b128 v[202:205], v170 offset:16384
	ds_read_b128 v[206:209], v170 offset:17408
	ds_read_b128 v[210:213], v170 offset:18432
	ds_read_b128 v[214:217], v170 offset:19456
	ds_read_b128 v[218:221], v170 offset:20480
	ds_read_b128 v[222:225], v170 offset:21504
	ds_read_b128 v[226:229], v170 offset:22528
	ds_read_b128 v[230:233], v170 offset:23552
	global_load_lds_dwordx4 v[176:177], off
	s_add_i32 m0, s21, 0x2000
	v_lshl_add_u64 v[234:235], s[14:15], 0, v[152:153]
	s_add_u32 s14, s14, s28
	s_addc_u32 s15, s15, 0
	s_add_i32 s20, s20, s79
	global_load_lds_dwordx4 v[234:235], off
	v_lshl_add_u64 v[236:237], s[14:15], 0, v[148:149]
	s_mov_b32 m0, s20
	v_lshl_add_u64 v[238:239], s[14:15], 0, v[152:153]
	global_load_lds_dwordx4 v[236:237], off
	s_add_i32 m0, s20, 0x2000
	v_lshl_add_u64 v[240:241], s[18:19], 0, v[146:147]
	global_load_lds_dwordx4 v[238:239], off
	s_mov_b32 m0, s80
	v_lshl_add_u64 v[242:243], s[18:19], 0, v[150:151]
	global_load_lds_dwordx4 v[240:241], off
	s_mov_b32 m0, s81
	s_nop 0
	global_load_lds_dwordx4 v[242:243], off
	s_waitcnt vmcnt(8) lgkmcnt(0)
	s_barrier
; #define PG8_STAGE(bufoff, gbase, voff) do { _Pragma("unroll") for (int _i = 0; _i < 2; ++_i) \
;         __builtin_amdgcn_global_load_lds((const unsigned*)((const char*)(gbase) + (voff)[_i]), (PG8_LAS unsigned*)(lds + (bufoff) + ldsw + _i * 8192), 16, 0, 0); } while (0)
; #define PG8_LDA(dst, b, h) do { _Pragma("unroll") for (int m = 0; m < 4; ++m) _Pragma("unroll") for (int k = 0; k < 2; ++k) dst[m][k] = *(const PG8_LAS bf16x8*)(lds + PG8_SA(b, h) + aoff + m * 2048 + k * 1024); } while (0)
; #define PG8_LDB(dst, b, h) do { _Pragma("unroll") for (int n = 0; n < 2; ++n) _Pragma("unroll") for (int k = 0; k < 2; ++k) dst[n][k] = *(const PG8_LAS bf16x8*)(lds + PG8_SB(b, h) + boff + n * 2048 + k * 1024); } while (0)
; #define PG8_MMA(ai, bj, At, Bt) do { __builtin_amdgcn_s_setprio(1); _Pragma("unroll") for (int m = 0; m < 4; ++m) _Pragma("unroll") for (int n = 0; n < 2; ++n) _Pragma("unroll") for (int k = 0; k < 2; ++k) \
;         acc[ai][bj][m][n] = __builtin_amdgcn_mfma_f32_16x16x32_bf16(Bt[n][k], At[m][k], acc[ai][bj][m][n], 0, 0, 0); __builtin_amdgcn_s_setprio(0); } while (0)
; #define PG8_WAIT_V(n) asm volatile("s_waitcnt vmcnt(" #n ")" ::: "memory")
; #define PG8_WAIT_L(n) asm volatile("s_waitcnt lgkmcnt(" #n ")" ::: "memory")
; #define PG8_BAR __builtin_amdgcn_s_barrier()
; #define PG8_SCHED __builtin_amdgcn_sched_barrier(0)
; template <class Epi, class Sched, bool ALIGN_EPI = false, bool SP2 = false>
; __device__ __forceinline__ void gemm_phase(PG8_LAS unsigned char* lds, const Gemm g, const Sched S, const Epi E) {
;     ...
;             PG8_WAIT_V(8); PG8_WAIT_L(0); PG8_BAR; PG8_MMA(1, 0, At, B0); PG8_MMA(1, 1, At, B1); PG8_BAR; PG8_SCHED;
;             PG8_LDB(B0, 1, 0); PG8_LDB(B1, 1, 1); PG8_SCHED; PG8_LDA(At, 1, 0); PG8_STAGE(PG8_SA(0, 1), a2 + hstep, voffA);
;             PG8_WAIT_V(8); PG8_WAIT_L(0); PG8_BAR; PG8_MMA(0, 0, At, B0); PG8_MMA(0, 1, At, B1); PG8_BAR; PG8_SCHED;
	s_setprio 1
	v_mfma_f32_16x16x32_bf16 v[70:73], v[134:137], v[202:205], v[70:73]
	v_mfma_f32_16x16x32_bf16 v[66:69], v[142:145], v[202:205], v[66:69]
	v_mfma_f32_16x16x32_bf16 v[86:89], v[134:137], v[210:213], v[86:89]
	v_mfma_f32_16x16x32_bf16 v[82:85], v[142:145], v[210:213], v[82:85]
	v_mfma_f32_16x16x32_bf16 v[102:105], v[134:137], v[218:221], v[102:105]
	v_mfma_f32_16x16x32_bf16 v[98:101], v[142:145], v[218:221], v[98:101]
	v_mfma_f32_16x16x32_bf16 v[118:121], v[134:137], v[226:229], v[118:121]
	v_mfma_f32_16x16x32_bf16 v[114:117], v[142:145], v[226:229], v[114:117]
	v_mfma_f32_16x16x32_bf16 v[70:73], v[138:141], v[206:209], v[70:73]
	v_mfma_f32_16x16x32_bf16 v[66:69], v[158:161], v[206:209], v[66:69]
	v_mfma_f32_16x16x32_bf16 v[86:89], v[138:141], v[214:217], v[86:89]
	v_mfma_f32_16x16x32_bf16 v[82:85], v[158:161], v[214:217], v[82:85]
	v_mfma_f32_16x16x32_bf16 v[102:105], v[138:141], v[222:225], v[102:105]
	v_mfma_f32_16x16x32_bf16 v[98:101], v[158:161], v[222:225], v[98:101]
	v_mfma_f32_16x16x32_bf16 v[118:121], v[138:141], v[230:233], v[118:121]
	v_mfma_f32_16x16x32_bf16 v[114:117], v[158:161], v[230:233], v[114:117]
	s_setprio 0
	s_setprio 1
	v_mfma_f32_16x16x32_bf16 v[78:81], v[162:165], v[202:205], v[78:81]
	v_mfma_f32_16x16x32_bf16 v[74:77], v[182:185], v[202:205], v[74:77]
	v_mfma_f32_16x16x32_bf16 v[94:97], v[162:165], v[210:213], v[94:97]
	v_mfma_f32_16x16x32_bf16 v[90:93], v[182:185], v[210:213], v[90:93]
	v_mfma_f32_16x16x32_bf16 v[110:113], v[162:165], v[218:221], v[110:113]
	v_mfma_f32_16x16x32_bf16 v[106:109], v[182:185], v[218:221], v[106:109]
	v_mfma_f32_16x16x32_bf16 v[126:129], v[162:165], v[226:229], v[126:129]
	v_mfma_f32_16x16x32_bf16 v[122:125], v[182:185], v[226:229], v[122:125]
	v_mfma_f32_16x16x32_bf16 v[78:81], v[172:175], v[206:209], v[78:81]
	v_mfma_f32_16x16x32_bf16 v[74:77], v[198:201], v[206:209], v[74:77]
	v_mfma_f32_16x16x32_bf16 v[94:97], v[172:175], v[214:217], v[94:97]
	v_mfma_f32_16x16x32_bf16 v[90:93], v[198:201], v[214:217], v[90:93]
	v_mfma_f32_16x16x32_bf16 v[110:113], v[172:175], v[222:225], v[110:113]
	v_mfma_f32_16x16x32_bf16 v[106:109], v[198:201], v[222:225], v[106:109]
	v_mfma_f32_16x16x32_bf16 v[126:129], v[172:175], v[230:233], v[126:129]
	v_mfma_f32_16x16x32_bf16 v[122:125], v[198:201], v[230:233], v[122:125]
	s_setprio 0
	s_barrier
	v_add_u32_e32 v158, 0x18000, v168
	v_add_u32_e32 v171, 0x1c000, v168
	ds_read_b128 v[134:137], v158
	ds_read_b128 v[138:141], v158 offset:1024
	ds_read_b128 v[142:145], v158 offset:2048
	ds_read_b128 v[158:161], v158 offset:3072
	ds_read_b128 v[162:165], v171
	ds_read_b128 v[172:175], v171 offset:1024
	ds_read_b128 v[182:185], v171 offset:2048
	ds_read_b128 v[198:201], v171 offset:3072
	s_add_i32 s20, 0, 0x18000
	s_add_i32 s21, 0, 0x1c000
	s_add_u32 s14, s18, s28
	s_addc_u32 s15, s19, 0
	s_mov_b32 m0, s82
	v_lshl_add_u64 v[244:245], s[14:15], 0, v[146:147]
	ds_read_b128 v[202:205], v170 offset:32768
	ds_read_b128 v[206:209], v170 offset:33792
	ds_read_b128 v[210:213], v170 offset:34816
	ds_read_b128 v[214:217], v170 offset:35840
	ds_read_b128 v[218:221], v170 offset:36864
	ds_read_b128 v[222:225], v170 offset:37888
	ds_read_b128 v[226:229], v170 offset:38912
	ds_read_b128 v[230:233], v170 offset:39936
	global_load_lds_dwordx4 v[244:245], off
	v_lshl_add_u64 v[244:245], s[14:15], 0, v[150:151]
	s_mov_b32 m0, s83
	s_nop 0
	global_load_lds_dwordx4 v[244:245], off
	s_waitcnt vmcnt(8) lgkmcnt(0)
	s_barrier
	s_setprio 1
	v_mfma_f32_16x16x32_bf16 v[58:61], v[134:137], v[202:205], v[58:61]
	v_mfma_f32_16x16x32_bf16 v[50:53], v[142:145], v[202:205], v[50:53]
	v_mfma_f32_16x16x32_bf16 v[14:17], v[134:137], v[210:213], v[14:17]
	v_mfma_f32_16x16x32_bf16 v[10:13], v[142:145], v[210:213], v[10:13]
	v_mfma_f32_16x16x32_bf16 v[30:33], v[134:137], v[218:221], v[30:33]
	v_mfma_f32_16x16x32_bf16 v[26:29], v[142:145], v[218:221], v[26:29]
	v_mfma_f32_16x16x32_bf16 v[46:49], v[134:137], v[226:229], v[46:49]
	v_mfma_f32_16x16x32_bf16 v[42:45], v[142:145], v[226:229], v[42:45]
	v_mfma_f32_16x16x32_bf16 v[58:61], v[138:141], v[206:209], v[58:61]
	v_mfma_f32_16x16x32_bf16 v[50:53], v[158:161], v[206:209], v[50:53]
	v_mfma_f32_16x16x32_bf16 v[14:17], v[138:141], v[214:217], v[14:17]
	v_mfma_f32_16x16x32_bf16 v[10:13], v[158:161], v[214:217], v[10:13]
	v_mfma_f32_16x16x32_bf16 v[30:33], v[138:141], v[222:225], v[30:33]
	v_mfma_f32_16x16x32_bf16 v[26:29], v[158:161], v[222:225], v[26:29]
	v_mfma_f32_16x16x32_bf16 v[46:49], v[138:141], v[230:233], v[46:49]
	v_mfma_f32_16x16x32_bf16 v[42:45], v[158:161], v[230:233], v[42:45]
	s_setprio 0
	s_setprio 1
	v_mfma_f32_16x16x32_bf16 v[6:9], v[162:165], v[202:205], v[6:9]
	v_mfma_f32_16x16x32_bf16 v[2:5], v[182:185], v[202:205], v[2:5]
	v_mfma_f32_16x16x32_bf16 v[22:25], v[162:165], v[210:213], v[22:25]
	v_mfma_f32_16x16x32_bf16 v[18:21], v[182:185], v[210:213], v[18:21]
	v_mfma_f32_16x16x32_bf16 v[38:41], v[162:165], v[218:221], v[38:41]
	v_mfma_f32_16x16x32_bf16 v[34:37], v[182:185], v[218:221], v[34:37]
	v_mfma_f32_16x16x32_bf16 v[62:65], v[162:165], v[226:229], v[62:65]
	v_mfma_f32_16x16x32_bf16 v[54:57], v[182:185], v[226:229], v[54:57]
	v_mfma_f32_16x16x32_bf16 v[6:9], v[172:175], v[206:209], v[6:9]
	v_mfma_f32_16x16x32_bf16 v[2:5], v[198:201], v[206:209], v[2:5]
	v_mfma_f32_16x16x32_bf16 v[22:25], v[172:175], v[214:217], v[22:25]
	v_mfma_f32_16x16x32_bf16 v[18:21], v[198:201], v[214:217], v[18:21]
	v_mfma_f32_16x16x32_bf16 v[38:41], v[172:175], v[222:225], v[38:41]
	v_mfma_f32_16x16x32_bf16 v[34:37], v[198:201], v[222:225], v[34:37]
	v_mfma_f32_16x16x32_bf16 v[62:65], v[172:175], v[230:233], v[62:65]
	v_mfma_f32_16x16x32_bf16 v[54:57], v[198:201], v[230:233], v[54:57]
	s_setprio 0
	s_barrier
; #define PG8_STAGE(bufoff, gbase, voff) do { _Pragma("unroll") for (int _i = 0; _i < 2; ++_i) \
;         __builtin_amdgcn_global_load_lds((const unsigned*)((const char*)(gbase) + (voff)[_i]), (PG8_LAS unsigned*)(lds + (bufoff) + ldsw + _i * 8192), 16, 0, 0); } while (0)
; #define PG8_LDA(dst, b, h) do { _Pragma("unroll") for (int m = 0; m < 4; ++m) _Pragma("unroll") for (int k = 0; k < 2; ++k) dst[m][k] = *(const PG8_LAS bf16x8*)(lds + PG8_SA(b, h) + aoff + m * 2048 + k * 1024); } while (0)
; #define PG8_MMA(ai, bj, At, Bt) do { __builtin_amdgcn_s_setprio(1); _Pragma("unroll") for (int m = 0; m < 4; ++m) _Pragma("unroll") for (int n = 0; n < 2; ++n) _Pragma("unroll") for (int k = 0; k < 2; ++k) \
;         acc[ai][bj][m][n] = __builtin_amdgcn_mfma_f32_16x16x32_bf16(Bt[n][k], At[m][k], acc[ai][bj][m][n], 0, 0, 0); __builtin_amdgcn_s_setprio(0); } while (0)
; #define PG8_WAIT_V(n) asm volatile("s_waitcnt vmcnt(" #n ")" ::: "memory")
; #define PG8_WAIT_L(n) asm volatile("s_waitcnt lgkmcnt(" #n ")" ::: "memory")
; #define PG8_BAR __builtin_amdgcn_s_barrier()
; #define PG8_SCHED __builtin_amdgcn_sched_barrier(0)
; template <class Epi, class Sched, bool ALIGN_EPI = false, bool SP2 = false>
; __device__ __forceinline__ void gemm_phase(PG8_LAS unsigned char* lds, const Gemm g, const Sched S, const Epi E) {
;     ...
;             PG8_LDA(At, 1, 1); PG8_STAGE(PG8_SB(1, 0), b3, voffB); PG8_STAGE(PG8_SB(1, 1), b3 + hstep, voffB); PG8_STAGE(PG8_SA(1, 0), a3, voffA);
;             PG8_WAIT_V(8); PG8_WAIT_L(0); PG8_BAR; PG8_MMA(1, 0, At, B0); PG8_MMA(1, 1, At, B1); PG8_BAR; PG8_SCHED;
	s_add_i32 s14, s20, s79
	v_lshl_add_u64 v[176:177], v[176:177], 0, s[12:13]
	s_mov_b32 m0, s14
	ds_read_b128 v[202:205], v170 offset:49152
	ds_read_b128 v[206:209], v170 offset:50176
	ds_read_b128 v[210:213], v170 offset:51200
	ds_read_b128 v[214:217], v170 offset:52224
	ds_read_b128 v[218:221], v170 offset:53248
	ds_read_b128 v[222:225], v170 offset:54272
	ds_read_b128 v[226:229], v170 offset:55296
	ds_read_b128 v[230:233], v170 offset:56320
	global_load_lds_dwordx4 v[176:177], off
	v_lshl_add_u64 v[176:177], v[234:235], 0, s[12:13]
	s_add_i32 m0, s14, 0x2000
	s_add_i32 s14, s21, s79
	global_load_lds_dwordx4 v[176:177], off
	v_lshl_add_u64 v[176:177], v[236:237], 0, s[12:13]
	s_mov_b32 m0, s14
	s_nop 0
	global_load_lds_dwordx4 v[176:177], off
	v_lshl_add_u64 v[176:177], v[238:239], 0, s[12:13]
	s_add_i32 m0, s14, 0x2000
	s_nop 0
	global_load_lds_dwordx4 v[176:177], off
	v_lshl_add_u64 v[176:177], v[240:241], 0, s[12:13]
	s_mov_b32 m0, s84
	s_nop 0
	global_load_lds_dwordx4 v[176:177], off
	v_lshl_add_u64 v[176:177], v[242:243], 0, s[12:13]
	s_mov_b32 m0, s85
	s_nop 0
	global_load_lds_dwordx4 v[176:177], off
	s_waitcnt vmcnt(8) lgkmcnt(0)
	s_barrier
	s_setprio 1
	v_mfma_f32_16x16x32_bf16 v[70:73], v[134:137], v[202:205], v[70:73]
	v_mfma_f32_16x16x32_bf16 v[66:69], v[142:145], v[202:205], v[66:69]
	v_mfma_f32_16x16x32_bf16 v[86:89], v[134:137], v[210:213], v[86:89]
	v_mfma_f32_16x16x32_bf16 v[82:85], v[142:145], v[210:213], v[82:85]
	v_mfma_f32_16x16x32_bf16 v[102:105], v[134:137], v[218:221], v[102:105]
	v_mfma_f32_16x16x32_bf16 v[98:101], v[142:145], v[218:221], v[98:101]
	v_mfma_f32_16x16x32_bf16 v[118:121], v[134:137], v[226:229], v[118:121]
	v_mfma_f32_16x16x32_bf16 v[114:117], v[142:145], v[226:229], v[114:117]
	v_mfma_f32_16x16x32_bf16 v[70:73], v[138:141], v[206:209], v[70:73]
	v_mfma_f32_16x16x32_bf16 v[66:69], v[158:161], v[206:209], v[66:69]
	v_mfma_f32_16x16x32_bf16 v[86:89], v[138:141], v[214:217], v[86:89]
	v_mfma_f32_16x16x32_bf16 v[82:85], v[158:161], v[214:217], v[82:85]
	v_mfma_f32_16x16x32_bf16 v[102:105], v[138:141], v[222:225], v[102:105]
	v_mfma_f32_16x16x32_bf16 v[98:101], v[158:161], v[222:225], v[98:101]
	v_mfma_f32_16x16x32_bf16 v[118:121], v[138:141], v[230:233], v[118:121]
	v_mfma_f32_16x16x32_bf16 v[114:117], v[158:161], v[230:233], v[114:117]
	s_setprio 0
	s_setprio 1
	v_mfma_f32_16x16x32_bf16 v[78:81], v[162:165], v[202:205], v[78:81]
	v_mfma_f32_16x16x32_bf16 v[74:77], v[182:185], v[202:205], v[74:77]
	v_mfma_f32_16x16x32_bf16 v[94:97], v[162:165], v[210:213], v[94:97]
	v_mfma_f32_16x16x32_bf16 v[90:93], v[182:185], v[210:213], v[90:93]
	v_mfma_f32_16x16x32_bf16 v[110:113], v[162:165], v[218:221], v[110:113]
	v_mfma_f32_16x16x32_bf16 v[106:109], v[182:185], v[218:221], v[106:109]
	v_mfma_f32_16x16x32_bf16 v[126:129], v[162:165], v[226:229], v[126:129]
	v_mfma_f32_16x16x32_bf16 v[122:125], v[182:185], v[226:229], v[122:125]
	v_mfma_f32_16x16x32_bf16 v[78:81], v[172:175], v[206:209], v[78:81]
	v_mfma_f32_16x16x32_bf16 v[74:77], v[198:201], v[206:209], v[74:77]
	v_mfma_f32_16x16x32_bf16 v[94:97], v[172:175], v[214:217], v[94:97]
	v_mfma_f32_16x16x32_bf16 v[90:93], v[198:201], v[214:217], v[90:93]
	v_mfma_f32_16x16x32_bf16 v[110:113], v[172:175], v[222:225], v[110:113]
	v_mfma_f32_16x16x32_bf16 v[106:109], v[198:201], v[222:225], v[106:109]
	v_mfma_f32_16x16x32_bf16 v[126:129], v[172:175], v[230:233], v[126:129]
	v_mfma_f32_16x16x32_bf16 v[122:125], v[198:201], v[230:233], v[122:125]
	s_setprio 0
	s_add_u32 s16, s16, 0x100
	s_addc_u32 s17, s17, 0
	v_lshl_add_u64 v[132:133], v[132:133], 0, s[30:31]
	v_lshl_add_u64 v[130:131], v[130:131], 0, s[30:31]
	s_cmp_ge_u32 s3, s88
	s_mov_b32 s14, s3
	s_barrier
	s_cbranch_scc0 .LBB0_416
	s_and_b64 vcc, exec, s[62:63]
	s_cbranch_vccz .LBB0_419
	s_barrier

; #define PG8_STAGE(bufoff, gbase, voff) do { _Pragma("unroll") for (int _i = 0; _i < 2; ++_i) \
;         __builtin_amdgcn_global_load_lds((const unsigned*)((const char*)(gbase) + (voff)[_i]), (PG8_LAS unsigned*)(lds + (bufoff) + ldsw + _i * 8192), 16, 0, 0); } while (0)
; #define PG8_LDA(dst, b, h) do { _Pragma("unroll") for (int m = 0; m < 4; ++m) _Pragma("unroll") for (int k = 0; k < 2; ++k) dst[m][k] = *(const PG8_LAS bf16x8*)(lds + PG8_SA(b, h) + aoff + m * 2048 + k * 1024); } while (0)
; #define PG8_LDB(dst, b, h) do { _Pragma("unroll") for (int n = 0; n < 2; ++n) _Pragma("unroll") for (int k = 0; k < 2; ++k) dst[n][k] = *(const PG8_LAS bf16x8*)(lds + PG8_SB(b, h) + boff + n * 2048 + k * 1024); } while (0)
; #define PG8_MMA(ai, bj, At, Bt) do { __builtin_amdgcn_s_setprio(1); _Pragma("unroll") for (int m = 0; m < 4; ++m) _Pragma("unroll") for (int n = 0; n < 2; ++n) _Pragma("unroll") for (int k = 0; k < 2; ++k) \
;         acc[ai][bj][m][n] = __builtin_amdgcn_mfma_f32_16x16x32_bf16(Bt[n][k], At[m][k], acc[ai][bj][m][n], 0, 0, 0); __builtin_amdgcn_s_setprio(0); } while (0)
; #define PG8_WAIT_V(n) asm volatile("s_waitcnt vmcnt(" #n ")" ::: "memory")
; #define PG8_WAIT_L(n) asm volatile("s_waitcnt lgkmcnt(" #n ")" ::: "memory")
; #define PG8_BAR __builtin_amdgcn_s_barrier()
; #define PG8_SCHED __builtin_amdgcn_sched_barrier(0)
; template <class Epi, class Sched, bool ALIGN_EPI = false, bool SP2 = false>
; __device__ __forceinline__ void gemm_phase(PG8_LAS unsigned char* lds, const Gemm g, const Sched S, const Epi E) {
;     ...
;             PG8_LDB(B0, 0, 0); PG8_LDB(B1, 0, 1); PG8_SCHED; PG8_LDA(At, 0, 0); PG8_STAGE(PG8_SA(1, 1), a1 + hstep, voffA);
;             PG8_WAIT_V(8); PG8_WAIT_L(0); PG8_BAR; PG8_MMA(0, 0, At, B0); PG8_MMA(0, 1, At, B1); PG8_BAR; PG8_SCHED;
;             PG8_LDA(At, 0, 1); PG8_STAGE(PG8_SB(0, 0), b2, voffB); PG8_STAGE(PG8_SB(0, 1), b2 + hstep, voffB); PG8_STAGE(PG8_SA(0, 0), a2, voffA);
;             PG8_WAIT_V(8); PG8_WAIT_L(0); PG8_BAR; PG8_MMA(1, 0, At, B0); PG8_MMA(1, 1, At, B1); PG8_BAR; PG8_SCHED;
.LBB0_538:
	v_add_u32_e32 v155, 0x10000, v152
	ds_read_b128 v[146:149], v155
	ds_read_b128 v[156:159], v155 offset:1024
	ds_read_b128 v[160:163], v155 offset:2048
	ds_read_b128 v[164:167], v155 offset:3072
	v_add_u32_e32 v155, 0x14000, v152
	ds_read_b128 v[168:171], v155
	ds_read_b128 v[172:175], v155 offset:1024
	ds_read_b128 v[182:185], v155 offset:2048
	ds_read_b128 v[198:201], v155 offset:3072
	s_add_i32 s3, s14, 2
	s_add_u32 s15, s68, s16
	s_addc_u32 s18, s69, s17
	s_add_u32 s20, s66, s16
	s_addc_u32 s21, s67, s17
	s_add_i32 s22, 0, 0x10000
	s_cmp_eq_u32 s81, s14
	s_cselect_b32 s19, s1, s18
	s_cselect_b32 s18, s0, s15
	s_cselect_b32 s15, s55, s21
	s_cselect_b32 s14, s54, s20
	s_add_i32 s20, 0, 0x14000
	v_lshl_add_u64 v[176:177], s[68:69], 0, v[144:145]
	s_add_i32 m0, s72, 0xc000
	ds_read_b128 v[202:205], v154
	ds_read_b128 v[206:209], v154 offset:1024
	ds_read_b128 v[210:213], v154 offset:2048
	ds_read_b128 v[214:217], v154 offset:3072
	ds_read_b128 v[218:221], v154 offset:4096
	ds_read_b128 v[222:225], v154 offset:5120
	ds_read_b128 v[226:229], v154 offset:6144
	ds_read_b128 v[230:233], v154 offset:7168
	global_load_lds_dwordx4 v[176:177], off
	v_lshl_add_u64 v[176:177], s[68:69], 0, v[142:143]
	s_add_i32 m0, s72, 0xe000
	s_nop 0
	global_load_lds_dwordx4 v[176:177], off
	s_waitcnt vmcnt(8) lgkmcnt(0)
	s_barrier
	s_setprio 1
	v_mfma_f32_16x16x32_bf16 v[62:65], v[146:149], v[202:205], v[62:65]
	v_mfma_f32_16x16x32_bf16 v[54:57], v[160:163], v[202:205], v[54:57]
	v_mfma_f32_16x16x32_bf16 v[14:17], v[146:149], v[210:213], v[14:17]
	v_mfma_f32_16x16x32_bf16 v[10:13], v[160:163], v[210:213], v[10:13]
	v_mfma_f32_16x16x32_bf16 v[30:33], v[146:149], v[218:221], v[30:33]
	v_mfma_f32_16x16x32_bf16 v[26:29], v[160:163], v[218:221], v[26:29]
	v_mfma_f32_16x16x32_bf16 v[46:49], v[146:149], v[226:229], v[46:49]
	v_mfma_f32_16x16x32_bf16 v[42:45], v[160:163], v[226:229], v[42:45]
	v_mfma_f32_16x16x32_bf16 v[62:65], v[156:159], v[206:209], v[62:65]
	v_mfma_f32_16x16x32_bf16 v[54:57], v[164:167], v[206:209], v[54:57]
	v_mfma_f32_16x16x32_bf16 v[14:17], v[156:159], v[214:217], v[14:17]
	v_mfma_f32_16x16x32_bf16 v[10:13], v[164:167], v[214:217], v[10:13]
	v_mfma_f32_16x16x32_bf16 v[30:33], v[156:159], v[222:225], v[30:33]
	v_mfma_f32_16x16x32_bf16 v[26:29], v[164:167], v[222:225], v[26:29]
	v_mfma_f32_16x16x32_bf16 v[46:49], v[156:159], v[230:233], v[46:49]
	v_mfma_f32_16x16x32_bf16 v[42:45], v[164:167], v[230:233], v[42:45]
	s_setprio 0
	s_setprio 1
	v_mfma_f32_16x16x32_bf16 v[6:9], v[168:171], v[202:205], v[6:9]
	v_mfma_f32_16x16x32_bf16 v[2:5], v[182:185], v[202:205], v[2:5]
	v_mfma_f32_16x16x32_bf16 v[22:25], v[168:171], v[210:213], v[22:25]
	v_mfma_f32_16x16x32_bf16 v[18:21], v[182:185], v[210:213], v[18:21]
	v_mfma_f32_16x16x32_bf16 v[38:41], v[168:171], v[218:221], v[38:41]
	v_mfma_f32_16x16x32_bf16 v[34:37], v[182:185], v[218:221], v[34:37]
	v_mfma_f32_16x16x32_bf16 v[58:61], v[168:171], v[226:229], v[58:61]
	v_mfma_f32_16x16x32_bf16 v[50:53], v[182:185], v[226:229], v[50:53]
	v_mfma_f32_16x16x32_bf16 v[6:9], v[172:175], v[206:209], v[6:9]
	v_mfma_f32_16x16x32_bf16 v[2:5], v[198:201], v[206:209], v[2:5]
	v_mfma_f32_16x16x32_bf16 v[22:25], v[172:175], v[214:217], v[22:25]
	v_mfma_f32_16x16x32_bf16 v[18:21], v[198:201], v[214:217], v[18:21]
	v_mfma_f32_16x16x32_bf16 v[38:41], v[172:175], v[222:225], v[38:41]
	v_mfma_f32_16x16x32_bf16 v[34:37], v[198:201], v[222:225], v[34:37]
	v_mfma_f32_16x16x32_bf16 v[58:61], v[172:175], v[230:233], v[58:61]
	v_mfma_f32_16x16x32_bf16 v[50:53], v[198:201], v[230:233], v[50:53]
	s_setprio 0
	s_barrier
	s_add_i32 s21, s22, s71
	v_lshl_add_u64 v[176:177], s[14:15], 0, v[0:1]
	s_mov_b32 m0, s21
	ds_read_b128 v[202:205], v154 offset:16384
	ds_read_b128 v[206:209], v154 offset:17408
	ds_read_b128 v[210:213], v154 offset:18432
	ds_read_b128 v[214:217], v154 offset:19456
	ds_read_b128 v[218:221], v154 offset:20480
	ds_read_b128 v[222:225], v154 offset:21504
	ds_read_b128 v[226:229], v154 offset:22528
	ds_read_b128 v[230:233], v154 offset:23552
	global_load_lds_dwordx4 v[176:177], off
	s_add_i32 m0, s21, 0x2000
	v_lshl_add_u64 v[234:235], s[14:15], 0, v[134:135]
	s_add_u32 s14, s14, s28
	s_addc_u32 s15, s15, 0
	s_add_i32 s20, s20, s71
	global_load_lds_dwordx4 v[234:235], off
	v_lshl_add_u64 v[236:237], s[14:15], 0, v[0:1]
	s_mov_b32 m0, s20
	v_lshl_add_u64 v[238:239], s[14:15], 0, v[134:135]
	global_load_lds_dwordx4 v[236:237], off
	s_add_i32 m0, s20, 0x2000
	v_lshl_add_u64 v[240:241], s[18:19], 0, v[130:131]
	global_load_lds_dwordx4 v[238:239], off
	s_mov_b32 m0, s72
	v_lshl_add_u64 v[242:243], s[18:19], 0, v[132:133]
	global_load_lds_dwordx4 v[240:241], off
	s_mov_b32 m0, s73
	s_nop 0
	global_load_lds_dwordx4 v[242:243], off
	s_waitcnt vmcnt(8) lgkmcnt(0)
	s_barrier
; #define PG8_STAGE(bufoff, gbase, voff) do { _Pragma("unroll") for (int _i = 0; _i < 2; ++_i) \
;         __builtin_amdgcn_global_load_lds((const unsigned*)((const char*)(gbase) + (voff)[_i]), (PG8_LAS unsigned*)(lds + (bufoff) + ldsw + _i * 8192), 16, 0, 0); } while (0)
; #define PG8_LDA(dst, b, h) do { _Pragma("unroll") for (int m = 0; m < 4; ++m) _Pragma("unroll") for (int k = 0; k < 2; ++k) dst[m][k] = *(const PG8_LAS bf16x8*)(lds + PG8_SA(b, h) + aoff + m * 2048 + k * 1024); } while (0)
; #define PG8_LDB(dst, b, h) do { _Pragma("unroll") for (int n = 0; n < 2; ++n) _Pragma("unroll") for (int k = 0; k < 2; ++k) dst[n][k] = *(const PG8_LAS bf16x8*)(lds + PG8_SB(b, h) + boff + n * 2048 + k * 1024); } while (0)
; #define PG8_MMA(ai, bj, At, Bt) do { __builtin_amdgcn_s_setprio(1); _Pragma("unroll") for (int m = 0; m < 4; ++m) _Pragma("unroll") for (int n = 0; n < 2; ++n) _Pragma("unroll") for (int k = 0; k < 2; ++k) \
;         acc[ai][bj][m][n] = __builtin_amdgcn_mfma_f32_16x16x32_bf16(Bt[n][k], At[m][k], acc[ai][bj][m][n], 0, 0, 0); __builtin_amdgcn_s_setprio(0); } while (0)
; #define PG8_WAIT_V(n) asm volatile("s_waitcnt vmcnt(" #n ")" ::: "memory")
; #define PG8_WAIT_L(n) asm volatile("s_waitcnt lgkmcnt(" #n ")" ::: "memory")
; #define PG8_BAR __builtin_amdgcn_s_barrier()
; #define PG8_SCHED __builtin_amdgcn_sched_barrier(0)
; template <class Epi, class Sched, bool ALIGN_EPI = false, bool SP2 = false>
; __device__ __forceinline__ void gemm_phase(PG8_LAS unsigned char* lds, const Gemm g, const Sched S, const Epi E) {
;     ...
;             PG8_WAIT_V(8); PG8_WAIT_L(0); PG8_BAR; PG8_MMA(1, 0, At, B0); PG8_MMA(1, 1, At, B1); PG8_BAR; PG8_SCHED;
;             PG8_LDB(B0, 1, 0); PG8_LDB(B1, 1, 1); PG8_SCHED; PG8_LDA(At, 1, 0); PG8_STAGE(PG8_SA(0, 1), a2 + hstep, voffA);
;             PG8_WAIT_V(8); PG8_WAIT_L(0); PG8_BAR; PG8_MMA(0, 0, At, B0); PG8_MMA(0, 1, At, B1); PG8_BAR; PG8_SCHED;
	s_setprio 1
	v_mfma_f32_16x16x32_bf16 v[70:73], v[146:149], v[202:205], v[70:73]
	v_mfma_f32_16x16x32_bf16 v[66:69], v[160:163], v[202:205], v[66:69]
	v_mfma_f32_16x16x32_bf16 v[86:89], v[146:149], v[210:213], v[86:89]
	v_mfma_f32_16x16x32_bf16 v[82:85], v[160:163], v[210:213], v[82:85]
	v_mfma_f32_16x16x32_bf16 v[102:105], v[146:149], v[218:221], v[102:105]
	v_mfma_f32_16x16x32_bf16 v[98:101], v[160:163], v[218:221], v[98:101]
	v_mfma_f32_16x16x32_bf16 v[118:121], v[146:149], v[226:229], v[118:121]
	v_mfma_f32_16x16x32_bf16 v[114:117], v[160:163], v[226:229], v[114:117]
	v_mfma_f32_16x16x32_bf16 v[70:73], v[156:159], v[206:209], v[70:73]
	v_mfma_f32_16x16x32_bf16 v[66:69], v[164:167], v[206:209], v[66:69]
	v_mfma_f32_16x16x32_bf16 v[86:89], v[156:159], v[214:217], v[86:89]
	v_mfma_f32_16x16x32_bf16 v[82:85], v[164:167], v[214:217], v[82:85]
	v_mfma_f32_16x16x32_bf16 v[102:105], v[156:159], v[222:225], v[102:105]
	v_mfma_f32_16x16x32_bf16 v[98:101], v[164:167], v[222:225], v[98:101]
	v_mfma_f32_16x16x32_bf16 v[118:121], v[156:159], v[230:233], v[118:121]
	v_mfma_f32_16x16x32_bf16 v[114:117], v[164:167], v[230:233], v[114:117]
	s_setprio 0
	s_setprio 1
	v_mfma_f32_16x16x32_bf16 v[78:81], v[168:171], v[202:205], v[78:81]
	v_mfma_f32_16x16x32_bf16 v[74:77], v[182:185], v[202:205], v[74:77]
	v_mfma_f32_16x16x32_bf16 v[94:97], v[168:171], v[210:213], v[94:97]
	v_mfma_f32_16x16x32_bf16 v[90:93], v[182:185], v[210:213], v[90:93]
	v_mfma_f32_16x16x32_bf16 v[110:113], v[168:171], v[218:221], v[110:113]
	v_mfma_f32_16x16x32_bf16 v[106:109], v[182:185], v[218:221], v[106:109]
	v_mfma_f32_16x16x32_bf16 v[126:129], v[168:171], v[226:229], v[126:129]
	v_mfma_f32_16x16x32_bf16 v[122:125], v[182:185], v[226:229], v[122:125]
	v_mfma_f32_16x16x32_bf16 v[78:81], v[172:175], v[206:209], v[78:81]
	v_mfma_f32_16x16x32_bf16 v[74:77], v[198:201], v[206:209], v[74:77]
	v_mfma_f32_16x16x32_bf16 v[94:97], v[172:175], v[214:217], v[94:97]
	v_mfma_f32_16x16x32_bf16 v[90:93], v[198:201], v[214:217], v[90:93]
	v_mfma_f32_16x16x32_bf16 v[110:113], v[172:175], v[222:225], v[110:113]
	v_mfma_f32_16x16x32_bf16 v[106:109], v[198:201], v[222:225], v[106:109]
	v_mfma_f32_16x16x32_bf16 v[126:129], v[172:175], v[230:233], v[126:129]
	v_mfma_f32_16x16x32_bf16 v[122:125], v[198:201], v[230:233], v[122:125]
	s_setprio 0
	s_barrier
	v_add_u32_e32 v155, 0x18000, v152
	ds_read_b128 v[146:149], v155
	ds_read_b128 v[156:159], v155 offset:1024
	ds_read_b128 v[160:163], v155 offset:2048
	ds_read_b128 v[164:167], v155 offset:3072
	v_add_u32_e32 v155, 0x1c000, v152
	ds_read_b128 v[168:171], v155
	ds_read_b128 v[172:175], v155 offset:1024
	ds_read_b128 v[182:185], v155 offset:2048
	ds_read_b128 v[198:201], v155 offset:3072
	s_add_i32 s20, 0, 0x18000
	s_add_i32 s21, 0, 0x1c000
	s_add_u32 s14, s18, s28
	s_addc_u32 s15, s19, 0
	s_mov_b32 m0, s74
	v_lshl_add_u64 v[244:245], s[14:15], 0, v[130:131]
	ds_read_b128 v[202:205], v154 offset:32768
	ds_read_b128 v[206:209], v154 offset:33792
	ds_read_b128 v[210:213], v154 offset:34816
	ds_read_b128 v[214:217], v154 offset:35840
	ds_read_b128 v[218:221], v154 offset:36864
	ds_read_b128 v[222:225], v154 offset:37888
	ds_read_b128 v[226:229], v154 offset:38912
	ds_read_b128 v[230:233], v154 offset:39936
	global_load_lds_dwordx4 v[244:245], off
	v_lshl_add_u64 v[244:245], s[14:15], 0, v[132:133]
	s_mov_b32 m0, s75
	s_nop 0
	global_load_lds_dwordx4 v[244:245], off
	s_waitcnt vmcnt(8) lgkmcnt(0)
	s_barrier
	s_setprio 1
	v_mfma_f32_16x16x32_bf16 v[62:65], v[146:149], v[202:205], v[62:65]
	v_mfma_f32_16x16x32_bf16 v[54:57], v[160:163], v[202:205], v[54:57]
	v_mfma_f32_16x16x32_bf16 v[14:17], v[146:149], v[210:213], v[14:17]
	v_mfma_f32_16x16x32_bf16 v[10:13], v[160:163], v[210:213], v[10:13]
	v_mfma_f32_16x16x32_bf16 v[30:33], v[146:149], v[218:221], v[30:33]
	v_mfma_f32_16x16x32_bf16 v[26:29], v[160:163], v[218:221], v[26:29]
	v_mfma_f32_16x16x32_bf16 v[46:49], v[146:149], v[226:229], v[46:49]
	v_mfma_f32_16x16x32_bf16 v[42:45], v[160:163], v[226:229], v[42:45]
	v_mfma_f32_16x16x32_bf16 v[62:65], v[156:159], v[206:209], v[62:65]
	v_mfma_f32_16x16x32_bf16 v[54:57], v[164:167], v[206:209], v[54:57]
	v_mfma_f32_16x16x32_bf16 v[14:17], v[156:159], v[214:217], v[14:17]
	v_mfma_f32_16x16x32_bf16 v[10:13], v[164:167], v[214:217], v[10:13]
	v_mfma_f32_16x16x32_bf16 v[30:33], v[156:159], v[222:225], v[30:33]
	v_mfma_f32_16x16x32_bf16 v[26:29], v[164:167], v[222:225], v[26:29]
	v_mfma_f32_16x16x32_bf16 v[46:49], v[156:159], v[230:233], v[46:49]
	v_mfma_f32_16x16x32_bf16 v[42:45], v[164:167], v[230:233], v[42:45]
	s_setprio 0
	s_setprio 1
	v_mfma_f32_16x16x32_bf16 v[6:9], v[168:171], v[202:205], v[6:9]
	v_mfma_f32_16x16x32_bf16 v[2:5], v[182:185], v[202:205], v[2:5]
	v_mfma_f32_16x16x32_bf16 v[22:25], v[168:171], v[210:213], v[22:25]
	v_mfma_f32_16x16x32_bf16 v[18:21], v[182:185], v[210:213], v[18:21]
	v_mfma_f32_16x16x32_bf16 v[38:41], v[168:171], v[218:221], v[38:41]
	v_mfma_f32_16x16x32_bf16 v[34:37], v[182:185], v[218:221], v[34:37]
	v_mfma_f32_16x16x32_bf16 v[58:61], v[168:171], v[226:229], v[58:61]
	v_mfma_f32_16x16x32_bf16 v[50:53], v[182:185], v[226:229], v[50:53]
	v_mfma_f32_16x16x32_bf16 v[6:9], v[172:175], v[206:209], v[6:9]
	v_mfma_f32_16x16x32_bf16 v[2:5], v[198:201], v[206:209], v[2:5]
	v_mfma_f32_16x16x32_bf16 v[22:25], v[172:175], v[214:217], v[22:25]
	v_mfma_f32_16x16x32_bf16 v[18:21], v[198:201], v[214:217], v[18:21]
	v_mfma_f32_16x16x32_bf16 v[38:41], v[172:175], v[222:225], v[38:41]
	v_mfma_f32_16x16x32_bf16 v[34:37], v[198:201], v[222:225], v[34:37]
	v_mfma_f32_16x16x32_bf16 v[58:61], v[172:175], v[230:233], v[58:61]
	v_mfma_f32_16x16x32_bf16 v[50:53], v[198:201], v[230:233], v[50:53]
	s_setprio 0
	s_barrier
; #define PG8_STAGE(bufoff, gbase, voff) do { _Pragma("unroll") for (int _i = 0; _i < 2; ++_i) \
;         __builtin_amdgcn_global_load_lds((const unsigned*)((const char*)(gbase) + (voff)[_i]), (PG8_LAS unsigned*)(lds + (bufoff) + ldsw + _i * 8192), 16, 0, 0); } while (0)
; #define PG8_LDA(dst, b, h) do { _Pragma("unroll") for (int m = 0; m < 4; ++m) _Pragma("unroll") for (int k = 0; k < 2; ++k) dst[m][k] = *(const PG8_LAS bf16x8*)(lds + PG8_SA(b, h) + aoff + m * 2048 + k * 1024); } while (0)
; #define PG8_MMA(ai, bj, At, Bt) do { __builtin_amdgcn_s_setprio(1); _Pragma("unroll") for (int m = 0; m < 4; ++m) _Pragma("unroll") for (int n = 0; n < 2; ++n) _Pragma("unroll") for (int k = 0; k < 2; ++k) \
;         acc[ai][bj][m][n] = __builtin_amdgcn_mfma_f32_16x16x32_bf16(Bt[n][k], At[m][k], acc[ai][bj][m][n], 0, 0, 0); __builtin_amdgcn_s_setprio(0); } while (0)
; #define PG8_WAIT_V(n) asm volatile("s_waitcnt vmcnt(" #n ")" ::: "memory")
; #define PG8_WAIT_L(n) asm volatile("s_waitcnt lgkmcnt(" #n ")" ::: "memory")
; #define PG8_BAR __builtin_amdgcn_s_barrier()
; #define PG8_SCHED __builtin_amdgcn_sched_barrier(0)
; template <class Epi, class Sched, bool ALIGN_EPI = false, bool SP2 = false>
; __device__ __forceinline__ void gemm_phase(PG8_LAS unsigned char* lds, const Gemm g, const Sched S, const Epi E) {
;     ...
;             PG8_LDA(At, 1, 1); PG8_STAGE(PG8_SB(1, 0), b3, voffB); PG8_STAGE(PG8_SB(1, 1), b3 + hstep, voffB); PG8_STAGE(PG8_SA(1, 0), a3, voffA);
;             PG8_WAIT_V(8); PG8_WAIT_L(0); PG8_BAR; PG8_MMA(1, 0, At, B0); PG8_MMA(1, 1, At, B1); PG8_BAR; PG8_SCHED;
	s_add_i32 s14, s20, s71
	v_lshl_add_u64 v[176:177], v[176:177], 0, s[12:13]
	s_mov_b32 m0, s14
	ds_read_b128 v[202:205], v154 offset:49152
	ds_read_b128 v[206:209], v154 offset:50176
	ds_read_b128 v[210:213], v154 offset:51200
	ds_read_b128 v[214:217], v154 offset:52224
	ds_read_b128 v[218:221], v154 offset:53248
	ds_read_b128 v[222:225], v154 offset:54272
	ds_read_b128 v[226:229], v154 offset:55296
	ds_read_b128 v[230:233], v154 offset:56320
	global_load_lds_dwordx4 v[176:177], off
	v_lshl_add_u64 v[176:177], v[234:235], 0, s[12:13]
	s_add_i32 m0, s14, 0x2000
	s_add_i32 s14, s21, s71
	global_load_lds_dwordx4 v[176:177], off
	v_lshl_add_u64 v[176:177], v[236:237], 0, s[12:13]
	s_mov_b32 m0, s14
	s_nop 0
	global_load_lds_dwordx4 v[176:177], off
	v_lshl_add_u64 v[176:177], v[238:239], 0, s[12:13]
	s_add_i32 m0, s14, 0x2000
	s_nop 0
	global_load_lds_dwordx4 v[176:177], off
	v_lshl_add_u64 v[176:177], v[240:241], 0, s[12:13]
	s_mov_b32 m0, s77
	s_nop 0
	global_load_lds_dwordx4 v[176:177], off
	v_lshl_add_u64 v[176:177], v[242:243], 0, s[12:13]
	s_mov_b32 m0, s78
	s_nop 0
	global_load_lds_dwordx4 v[176:177], off
	s_waitcnt vmcnt(8) lgkmcnt(0)
	s_barrier
	s_setprio 1
	v_mfma_f32_16x16x32_bf16 v[70:73], v[146:149], v[202:205], v[70:73]
	v_mfma_f32_16x16x32_bf16 v[66:69], v[160:163], v[202:205], v[66:69]
	v_mfma_f32_16x16x32_bf16 v[86:89], v[146:149], v[210:213], v[86:89]
	v_mfma_f32_16x16x32_bf16 v[82:85], v[160:163], v[210:213], v[82:85]
	v_mfma_f32_16x16x32_bf16 v[102:105], v[146:149], v[218:221], v[102:105]
	v_mfma_f32_16x16x32_bf16 v[98:101], v[160:163], v[218:221], v[98:101]
	v_mfma_f32_16x16x32_bf16 v[118:121], v[146:149], v[226:229], v[118:121]
	v_mfma_f32_16x16x32_bf16 v[114:117], v[160:163], v[226:229], v[114:117]
	v_mfma_f32_16x16x32_bf16 v[70:73], v[156:159], v[206:209], v[70:73]
	v_mfma_f32_16x16x32_bf16 v[66:69], v[164:167], v[206:209], v[66:69]
	v_mfma_f32_16x16x32_bf16 v[86:89], v[156:159], v[214:217], v[86:89]
	v_mfma_f32_16x16x32_bf16 v[82:85], v[164:167], v[214:217], v[82:85]
	v_mfma_f32_16x16x32_bf16 v[102:105], v[156:159], v[222:225], v[102:105]
	v_mfma_f32_16x16x32_bf16 v[98:101], v[164:167], v[222:225], v[98:101]
	v_mfma_f32_16x16x32_bf16 v[118:121], v[156:159], v[230:233], v[118:121]
	v_mfma_f32_16x16x32_bf16 v[114:117], v[164:167], v[230:233], v[114:117]
	s_setprio 0
	s_setprio 1
	v_mfma_f32_16x16x32_bf16 v[78:81], v[168:171], v[202:205], v[78:81]
	v_mfma_f32_16x16x32_bf16 v[74:77], v[182:185], v[202:205], v[74:77]
	v_mfma_f32_16x16x32_bf16 v[94:97], v[168:171], v[210:213], v[94:97]
	v_mfma_f32_16x16x32_bf16 v[90:93], v[182:185], v[210:213], v[90:93]
	v_mfma_f32_16x16x32_bf16 v[110:113], v[168:171], v[218:221], v[110:113]
	v_mfma_f32_16x16x32_bf16 v[106:109], v[182:185], v[218:221], v[106:109]
	v_mfma_f32_16x16x32_bf16 v[126:129], v[168:171], v[226:229], v[126:129]
	v_mfma_f32_16x16x32_bf16 v[122:125], v[182:185], v[226:229], v[122:125]
	v_mfma_f32_16x16x32_bf16 v[78:81], v[172:175], v[206:209], v[78:81]
	v_mfma_f32_16x16x32_bf16 v[74:77], v[198:201], v[206:209], v[74:77]
	v_mfma_f32_16x16x32_bf16 v[94:97], v[172:175], v[214:217], v[94:97]
	v_mfma_f32_16x16x32_bf16 v[90:93], v[198:201], v[214:217], v[90:93]
	v_mfma_f32_16x16x32_bf16 v[110:113], v[172:175], v[222:225], v[110:113]
	v_mfma_f32_16x16x32_bf16 v[106:109], v[198:201], v[222:225], v[106:109]
	v_mfma_f32_16x16x32_bf16 v[126:129], v[172:175], v[230:233], v[126:129]
	v_mfma_f32_16x16x32_bf16 v[122:125], v[198:201], v[230:233], v[122:125]
	s_setprio 0
	s_add_u32 s16, s16, 0x100
	s_addc_u32 s17, s17, 0
	v_lshl_add_u64 v[144:145], v[144:145], 0, s[88:89]
	v_lshl_add_u64 v[142:143], v[142:143], 0, s[88:89]
	s_cmp_ge_u32 s3, s76
	s_mov_b32 s14, s3
	s_barrier
	s_cbranch_scc0 .LBB0_538
	s_and_b64 vcc, exec, s[62:63]
	s_cbranch_vccz .LBB0_541
	s_barrier
